# RWKV scan: single accumulation chain for the two dot products (no combine adds, 66 instead of 68 instructions per token), on top of v32
# speedup vs baseline: 1.0031x; 1.0031x over previous
; #define LAS __attribute__((address_space(3)))
; __device__ __forceinline__ void rwkv_block(KP p, int o, int b, int hd, LAS unsigned char* lds, const bf16_t* P, bf16_t* YB) {
;     ...
;         for (int n = 0; n < 256; ++n) {
;             LAS float* B = (LAS float*)(lds + BUF0 + (n & 1) * BUFSZ);
;             LAS float* Wd = B; LAS float* KK = B + 1024; LAS float* BB = B + 2048; LAS float* KM = B + 3072; LAS float* Rr = B + 4096; LAS float* Vv = B + 5120; LAS float* Yy = B + 7168;
;             f32x2 sv[2][4];
; #pragma unroll
;             for (int a = 0; a < 2; ++a)
; #pragma unroll
;                 for (int j = 0; j < 4; ++j) sv[a][j] = s[a][j];
; #pragma unroll 1
;             for (int rep2 = 0; rep2 < ((DUP_MASK & 128) ? 2 : 1); ++rep2) {
;             if (rep2 == 1) {
; #pragma unroll
;                 for (int a = 0; a < 2; ++a)
; #pragma unroll
;                     for (int j = 0; j < 4; ++j) s[a][j] = sv[a][j];
;             }
; #pragma unroll
;             for (int tt = 0; tt < 16; ++tt) {
;                 const int o8 = tt * 64 + c * 8;
;                 const f32x4 ka = *(const LAS f32x4*)(KK + o8), kb = *(const LAS f32x4*)(KK + o8 + 4);
;                 const f32x4 wa = *(const LAS f32x4*)(Wd + o8), wb = *(const LAS f32x4*)(Wd + o8 + 4);
;                 const f32x4 ba = *(const LAS f32x4*)(BB + o8), bb = *(const LAS f32x4*)(BB + o8 + 4);
;                 const f32x4 ma = *(const LAS f32x4*)(KM + o8), mb = *(const LAS f32x4*)(KM + o8 + 4);
;                 const f32x4 ra = *(const LAS f32x4*)(Rr + o8), rb = *(const LAS f32x4*)(Rr + o8 + 4);
;                 const f32x2 v01 = *(const LAS f32x2*)(Vv + tt * 64 + 2 * rp);
;                 const f32x2 k2[4] = {{ka[0], ka[1]}, {ka[2], ka[3]}, {kb[0], kb[1]}, {kb[2], kb[3]}};
;                 const f32x2 w2[4] = {{wa[0], wa[1]}, {wa[2], wa[3]}, {wb[0], wb[1]}, {wb[2], wb[3]}};
;                 const f32x2 b2[4] = {{ba[0], ba[1]}, {ba[2], ba[3]}, {bb[0], bb[1]}, {bb[2], bb[3]}};
;                 const f32x2 m2[4] = {{ma[0], ma[1]}, {ma[2], ma[3]}, {mb[0], mb[1]}, {mb[2], mb[3]}};
;                 const f32x2 r2[4] = {{ra[0], ra[1]}, {ra[2], ra[3]}, {rb[0], rb[1]}, {rb[2], rb[3]}};
;                 f32x2 accA = s[0][0] * k2[0], accB = s[1][0] * k2[0], accA2 = s[0][2] * k2[2], accB2 = s[1][2] * k2[2];
.Lrk_scan_loop:
	s_bitcmp1_b32 s1, 0
	s_cselect_b32 s7, 0x8040, 0
	s_add_i32 s7, s7, 0xc300
	v_add_u32_e32 v180, s7, v182
	v_add_u32_e32 v181, s7, v183
	v_cndmask_b32_e32 v184, v185, v181, vcc
	ds_read_b128 v[64:67], v180 offset:4096
	ds_read_b128 v[68:71], v180 offset:4112
	ds_read_b64 v[104:105], v181 offset:20480
	ds_read_b128 v[88:91], v180 offset:12288
	ds_read_b128 v[92:95], v180 offset:12304
	ds_read_b128 v[72:75], v180 offset:0
	ds_read_b128 v[76:79], v180 offset:16
	ds_read_b128 v[80:83], v180 offset:8192
	ds_read_b128 v[84:87], v180 offset:8208
	ds_read_b128 v[96:99], v180 offset:16384
	ds_read_b128 v[100:103], v180 offset:16400
	s_waitcnt lgkmcnt(0)
	v_pk_mul_f32 v[20:21], v[2:3], v[64:65] op_sel_hi:[1,0]
	ds_read_b128 v[110:113], v180 offset:4352
	ds_read_b128 v[114:117], v180 offset:4368
	v_pk_fma_f32 v[20:21], v[4:5], v[64:65], v[20:21] op_sel:[0,1,0]
	ds_read_b64 v[150:151], v181 offset:20736
	ds_read_b128 v[134:137], v180 offset:12544
	v_pk_fma_f32 v[20:21], v[6:7], v[66:67], v[20:21] op_sel_hi:[1,0,1]
	ds_read_b128 v[138:141], v180 offset:12560
	ds_read_b128 v[118:121], v180 offset:256
	v_pk_fma_f32 v[20:21], v[8:9], v[66:67], v[20:21] op_sel:[0,1,0]
	ds_read_b128 v[122:125], v180 offset:272
	ds_read_b128 v[126:129], v180 offset:8448
	v_pk_fma_f32 v[20:21], v[10:11], v[68:69], v[20:21] op_sel_hi:[1,0,1]
	ds_read_b128 v[130:133], v180 offset:8464
	ds_read_b128 v[142:145], v180 offset:16640
	v_pk_fma_f32 v[20:21], v[12:13], v[68:69], v[20:21] op_sel:[0,1,0]
	ds_read_b128 v[146:149], v180 offset:16656
	v_pk_mul_f32 v[24:25], v[104:105], v[88:89] op_sel_hi:[1,0]
	v_pk_fma_f32 v[20:21], v[14:15], v[70:71], v[20:21] op_sel_hi:[1,0,1]
	v_pk_mul_f32 v[26:27], v[104:105], v[88:89] op_sel:[0,1]
	v_pk_fma_f32 v[24:25], v[2:3], v[72:73], v[24:25] op_sel_hi:[1,0,1]
	v_pk_fma_f32 v[20:21], v[16:17], v[70:71], v[20:21] op_sel:[0,1,0]
	v_pk_fma_f32 v[26:27], v[4:5], v[72:73], v[26:27] op_sel:[0,1,0]
	v_pk_mul_f32 v[28:29], v[104:105], v[90:91] op_sel_hi:[1,0]
	v_add_f32_dpp v20, v20, v20 quad_perm:[1,0,3,2] row_mask:0xf bank_mask:0xf bound_ctrl:1
	v_add_f32_dpp v21, v21, v21 quad_perm:[1,0,3,2] row_mask:0xf bank_mask:0xf bound_ctrl:1
	v_pk_fma_f32 v[28:29], v[6:7], v[74:75], v[28:29] op_sel_hi:[1,0,1]
	v_add_f32_dpp v20, v20, v20 quad_perm:[2,3,0,1] row_mask:0xf bank_mask:0xf bound_ctrl:1
	v_add_f32_dpp v21, v21, v21 quad_perm:[2,3,0,1] row_mask:0xf bank_mask:0xf bound_ctrl:1
	v_pk_mul_f32 v[30:31], v[104:105], v[90:91] op_sel:[0,1]
	v_add_f32_dpp v20, v20, v20 row_half_mirror row_mask:0xf bank_mask:0xf bound_ctrl:1
	v_add_f32_dpp v21, v21, v21 row_half_mirror row_mask:0xf bank_mask:0xf bound_ctrl:1
	v_pk_fma_f32 v[30:31], v[8:9], v[74:75], v[30:31] op_sel:[0,1,0]
	v_pk_mul_f32 v[32:33], v[104:105], v[92:93] op_sel_hi:[1,0]
	v_pk_fma_f32 v[2:3], v[20:21], v[80:81], v[24:25] op_sel_hi:[1,0,1]
	v_pk_fma_f32 v[4:5], v[20:21], v[80:81], v[26:27] op_sel:[0,1,0]
	v_pk_fma_f32 v[6:7], v[20:21], v[82:83], v[28:29] op_sel_hi:[1,0,1]
	v_pk_fma_f32 v[8:9], v[20:21], v[82:83], v[30:31] op_sel:[0,1,0]
	v_pk_fma_f32 v[32:33], v[10:11], v[76:77], v[32:33] op_sel_hi:[1,0,1]
	v_pk_mul_f32 v[34:35], v[104:105], v[92:93] op_sel:[0,1]
	v_pk_mul_f32 v[36:37], v[104:105], v[94:95] op_sel_hi:[1,0]
	v_pk_fma_f32 v[10:11], v[20:21], v[84:85], v[32:33] op_sel_hi:[1,0,1]
	v_pk_fma_f32 v[34:35], v[12:13], v[76:77], v[34:35] op_sel:[0,1,0]
	v_pk_fma_f32 v[36:37], v[14:15], v[78:79], v[36:37] op_sel_hi:[1,0,1]
	v_pk_mul_f32 v[38:39], v[104:105], v[94:95] op_sel:[0,1]
	v_pk_fma_f32 v[12:13], v[20:21], v[84:85], v[34:35] op_sel:[0,1,0]
	v_pk_fma_f32 v[14:15], v[20:21], v[86:87], v[36:37] op_sel_hi:[1,0,1]
	v_pk_fma_f32 v[38:39], v[16:17], v[78:79], v[38:39] op_sel:[0,1,0]
	v_pk_mul_f32 v[40:41], v[2:3], v[96:97] op_sel_hi:[1,0]
	v_pk_fma_f32 v[16:17], v[20:21], v[86:87], v[38:39] op_sel:[0,1,0]
	v_pk_fma_f32 v[40:41], v[4:5], v[96:97], v[40:41] op_sel:[0,1,0]
	v_pk_fma_f32 v[40:41], v[6:7], v[98:99], v[40:41] op_sel_hi:[1,0,1]
	v_pk_fma_f32 v[40:41], v[8:9], v[98:99], v[40:41] op_sel:[0,1,0]
	v_pk_fma_f32 v[40:41], v[10:11], v[100:101], v[40:41] op_sel_hi:[1,0,1]
	v_pk_fma_f32 v[40:41], v[12:13], v[100:101], v[40:41] op_sel:[0,1,0]
	v_pk_fma_f32 v[40:41], v[14:15], v[102:103], v[40:41] op_sel_hi:[1,0,1]
	v_pk_fma_f32 v[40:41], v[16:17], v[102:103], v[40:41] op_sel:[0,1,0]
	s_waitcnt lgkmcnt(0)
; __device__ __forceinline__ void rwkv_block(KP p, int o, int b, int hd, LAS unsigned char* lds, const bf16_t* P, bf16_t* YB) {
;     ...
;             for (int tt = 0; tt < 16; ++tt) {
;                 const int o8 = tt * 64 + c * 8;
;                 const f32x4 ka = *(const LAS f32x4*)(KK + o8), kb = *(const LAS f32x4*)(KK + o8 + 4);
;                 const f32x4 wa = *(const LAS f32x4*)(Wd + o8), wb = *(const LAS f32x4*)(Wd + o8 + 4);
;                 const f32x4 ba = *(const LAS f32x4*)(BB + o8), bb = *(const LAS f32x4*)(BB + o8 + 4);
;                 const f32x4 ma = *(const LAS f32x4*)(KM + o8), mb = *(const LAS f32x4*)(KM + o8 + 4);
;                 const f32x4 ra = *(const LAS f32x4*)(Rr + o8), rb = *(const LAS f32x4*)(Rr + o8 + 4);
;                 const f32x2 v01 = *(const LAS f32x2*)(Vv + tt * 64 + 2 * rp);
;                 const f32x2 k2[4] = {{ka[0], ka[1]}, {ka[2], ka[3]}, {kb[0], kb[1]}, {kb[2], kb[3]}};
;                 const f32x2 w2[4] = {{wa[0], wa[1]}, {wa[2], wa[3]}, {wb[0], wb[1]}, {wb[2], wb[3]}};
;                 const f32x2 b2[4] = {{ba[0], ba[1]}, {ba[2], ba[3]}, {bb[0], bb[1]}, {bb[2], bb[3]}};
;                 const f32x2 m2[4] = {{ma[0], ma[1]}, {ma[2], ma[3]}, {mb[0], mb[1]}, {mb[2], mb[3]}};
;                 const f32x2 r2[4] = {{ra[0], ra[1]}, {ra[2], ra[3]}, {rb[0], rb[1]}, {rb[2], rb[3]}};
;                 f32x2 accA = s[0][0] * k2[0], accB = s[1][0] * k2[0], accA2 = s[0][2] * k2[2], accB2 = s[1][2] * k2[2];
;                 accA = s[0][1] * k2[1] + accA; accB = s[1][1] * k2[1] + accB; accA2 = s[0][3] * k2[3] + accA2; accB2 = s[1][3] * k2[3] + accB2;
;                 accA = accA + accA2; accB = accB + accB2;
;                 float sa0 = accA.x + accA.y, sa1 = accB.x + accB.y;
;                 sa0 += dpp_f<0xB1>(sa0); sa1 += dpp_f<0xB1>(sa1);
;                 sa0 += dpp_f<0x4E>(sa0); sa1 += dpp_f<0x4E>(sa1);
;                 sa0 += dpp_f<0x141>(sa0); sa1 += dpp_f<0x141>(sa1);
;                 const f32x2 saA = {sa0, sa0}, saB = {sa1, sa1}, vA = {v01.x, v01.x}, vB = {v01.y, v01.y};
;                 f32x2 yA, yB;
; #pragma unroll
;                 for (int j = 0; j < 4; ++j) {
;                     f32x2 tA = vA * m2[j], tB = vB * m2[j];
;                     tA = saA * b2[j] + tA; tB = saB * b2[j] + tB;
;                     s[0][j] = s[0][j] * w2[j] + tA; s[1][j] = s[1][j] * w2[j] + tB;
	v_pk_mul_f32 v[20:21], v[2:3], v[110:111] op_sel_hi:[1,0]
	ds_read_b128 v[64:67], v180 offset:4608
	ds_read_b128 v[68:71], v180 offset:4624
	v_pk_fma_f32 v[20:21], v[4:5], v[110:111], v[20:21] op_sel:[0,1,0]
	ds_read_b64 v[104:105], v181 offset:20992
	ds_read_b128 v[88:91], v180 offset:12800
	v_pk_fma_f32 v[20:21], v[6:7], v[112:113], v[20:21] op_sel_hi:[1,0,1]
	ds_read_b128 v[92:95], v180 offset:12816
	ds_read_b128 v[72:75], v180 offset:512
	v_pk_fma_f32 v[20:21], v[8:9], v[112:113], v[20:21] op_sel:[0,1,0]
	ds_read_b128 v[76:79], v180 offset:528
	ds_read_b128 v[80:83], v180 offset:8704
	v_pk_fma_f32 v[20:21], v[10:11], v[114:115], v[20:21] op_sel_hi:[1,0,1]
	ds_read_b128 v[84:87], v180 offset:8720
	ds_read_b128 v[96:99], v180 offset:16896
	v_pk_fma_f32 v[20:21], v[12:13], v[114:115], v[20:21] op_sel:[0,1,0]
	ds_read_b128 v[100:103], v180 offset:16912
	v_add_f32_dpp v40, v40, v40 quad_perm:[1,0,3,2] row_mask:0xf bank_mask:0xf bound_ctrl:1
	v_pk_fma_f32 v[20:21], v[14:15], v[116:117], v[20:21] op_sel_hi:[1,0,1]
	v_add_f32_dpp v41, v41, v41 quad_perm:[1,0,3,2] row_mask:0xf bank_mask:0xf bound_ctrl:1
	v_add_f32_dpp v40, v40, v40 quad_perm:[2,3,0,1] row_mask:0xf bank_mask:0xf bound_ctrl:1
	v_pk_fma_f32 v[20:21], v[16:17], v[116:117], v[20:21] op_sel:[0,1,0]
	v_add_f32_dpp v41, v41, v41 quad_perm:[2,3,0,1] row_mask:0xf bank_mask:0xf bound_ctrl:1
	v_add_f32_dpp v40, v40, v40 row_half_mirror row_mask:0xf bank_mask:0xf bound_ctrl:1
	v_add_f32_dpp v20, v20, v20 quad_perm:[1,0,3,2] row_mask:0xf bank_mask:0xf bound_ctrl:1
	v_add_f32_dpp v21, v21, v21 quad_perm:[1,0,3,2] row_mask:0xf bank_mask:0xf bound_ctrl:1
	v_add_f32_dpp v41, v41, v41 row_half_mirror row_mask:0xf bank_mask:0xf bound_ctrl:1
	v_add_f32_dpp v20, v20, v20 quad_perm:[2,3,0,1] row_mask:0xf bank_mask:0xf bound_ctrl:1
	v_add_f32_dpp v21, v21, v21 quad_perm:[2,3,0,1] row_mask:0xf bank_mask:0xf bound_ctrl:1
	ds_write_b64 v184, v[40:41] offset:28672
	v_add_f32_dpp v20, v20, v20 row_half_mirror row_mask:0xf bank_mask:0xf bound_ctrl:1
	v_add_f32_dpp v21, v21, v21 row_half_mirror row_mask:0xf bank_mask:0xf bound_ctrl:1
	v_pk_mul_f32 v[24:25], v[150:151], v[134:135] op_sel_hi:[1,0]
	v_pk_mul_f32 v[26:27], v[150:151], v[134:135] op_sel:[0,1]
	v_pk_mul_f32 v[28:29], v[150:151], v[136:137] op_sel_hi:[1,0]
	v_pk_fma_f32 v[24:25], v[2:3], v[118:119], v[24:25] op_sel_hi:[1,0,1]
	v_pk_fma_f32 v[26:27], v[4:5], v[118:119], v[26:27] op_sel:[0,1,0]
	v_pk_fma_f32 v[28:29], v[6:7], v[120:121], v[28:29] op_sel_hi:[1,0,1]
	v_pk_fma_f32 v[2:3], v[20:21], v[126:127], v[24:25] op_sel_hi:[1,0,1]
	v_pk_fma_f32 v[4:5], v[20:21], v[126:127], v[26:27] op_sel:[0,1,0]
	v_pk_fma_f32 v[6:7], v[20:21], v[128:129], v[28:29] op_sel_hi:[1,0,1]
	v_pk_mul_f32 v[30:31], v[150:151], v[136:137] op_sel:[0,1]
	v_pk_mul_f32 v[32:33], v[150:151], v[138:139] op_sel_hi:[1,0]
	v_pk_mul_f32 v[34:35], v[150:151], v[138:139] op_sel:[0,1]
	v_pk_fma_f32 v[30:31], v[8:9], v[120:121], v[30:31] op_sel:[0,1,0]
	v_pk_fma_f32 v[32:33], v[10:11], v[122:123], v[32:33] op_sel_hi:[1,0,1]
	v_pk_fma_f32 v[34:35], v[12:13], v[122:123], v[34:35] op_sel:[0,1,0]
	v_pk_fma_f32 v[8:9], v[20:21], v[128:129], v[30:31] op_sel:[0,1,0]
	v_pk_fma_f32 v[10:11], v[20:21], v[130:131], v[32:33] op_sel_hi:[1,0,1]
	v_pk_fma_f32 v[12:13], v[20:21], v[130:131], v[34:35] op_sel:[0,1,0]
	v_pk_mul_f32 v[36:37], v[150:151], v[140:141] op_sel_hi:[1,0]
	v_pk_mul_f32 v[38:39], v[150:151], v[140:141] op_sel:[0,1]
	v_pk_mul_f32 v[42:43], v[2:3], v[142:143] op_sel_hi:[1,0]
	v_pk_fma_f32 v[36:37], v[14:15], v[124:125], v[36:37] op_sel_hi:[1,0,1]
	v_pk_fma_f32 v[38:39], v[16:17], v[124:125], v[38:39] op_sel:[0,1,0]
	v_pk_fma_f32 v[42:43], v[4:5], v[142:143], v[42:43] op_sel:[0,1,0]
	v_pk_fma_f32 v[14:15], v[20:21], v[132:133], v[36:37] op_sel_hi:[1,0,1]
	v_pk_fma_f32 v[16:17], v[20:21], v[132:133], v[38:39] op_sel:[0,1,0]
	v_pk_fma_f32 v[42:43], v[6:7], v[144:145], v[42:43] op_sel_hi:[1,0,1]
	v_pk_fma_f32 v[42:43], v[8:9], v[144:145], v[42:43] op_sel:[0,1,0]
	v_pk_fma_f32 v[42:43], v[10:11], v[146:147], v[42:43] op_sel_hi:[1,0,1]
	v_pk_fma_f32 v[42:43], v[12:13], v[146:147], v[42:43] op_sel:[0,1,0]
	v_pk_fma_f32 v[42:43], v[14:15], v[148:149], v[42:43] op_sel_hi:[1,0,1]
	v_pk_fma_f32 v[42:43], v[16:17], v[148:149], v[42:43] op_sel:[0,1,0]
	s_waitcnt lgkmcnt(0)
; __device__ __forceinline__ void rwkv_block(KP p, int o, int b, int hd, LAS unsigned char* lds, const bf16_t* P, bf16_t* YB) {
;     ...
;             for (int tt = 0; tt < 16; ++tt) {
;                 const int o8 = tt * 64 + c * 8;
;                 const f32x4 ka = *(const LAS f32x4*)(KK + o8), kb = *(const LAS f32x4*)(KK + o8 + 4);
;                 const f32x4 wa = *(const LAS f32x4*)(Wd + o8), wb = *(const LAS f32x4*)(Wd + o8 + 4);
;                 const f32x4 ba = *(const LAS f32x4*)(BB + o8), bb = *(const LAS f32x4*)(BB + o8 + 4);
;                 const f32x4 ma = *(const LAS f32x4*)(KM + o8), mb = *(const LAS f32x4*)(KM + o8 + 4);
;                 const f32x4 ra = *(const LAS f32x4*)(Rr + o8), rb = *(const LAS f32x4*)(Rr + o8 + 4);
;                 const f32x2 v01 = *(const LAS f32x2*)(Vv + tt * 64 + 2 * rp);
;                 const f32x2 k2[4] = {{ka[0], ka[1]}, {ka[2], ka[3]}, {kb[0], kb[1]}, {kb[2], kb[3]}};
;                 const f32x2 w2[4] = {{wa[0], wa[1]}, {wa[2], wa[3]}, {wb[0], wb[1]}, {wb[2], wb[3]}};
;                 const f32x2 b2[4] = {{ba[0], ba[1]}, {ba[2], ba[3]}, {bb[0], bb[1]}, {bb[2], bb[3]}};
;                 const f32x2 m2[4] = {{ma[0], ma[1]}, {ma[2], ma[3]}, {mb[0], mb[1]}, {mb[2], mb[3]}};
;                 const f32x2 r2[4] = {{ra[0], ra[1]}, {ra[2], ra[3]}, {rb[0], rb[1]}, {rb[2], rb[3]}};
;                 f32x2 accA = s[0][0] * k2[0], accB = s[1][0] * k2[0], accA2 = s[0][2] * k2[2], accB2 = s[1][2] * k2[2];
;                 accA = s[0][1] * k2[1] + accA; accB = s[1][1] * k2[1] + accB; accA2 = s[0][3] * k2[3] + accA2; accB2 = s[1][3] * k2[3] + accB2;
;                 accA = accA + accA2; accB = accB + accB2;
;                 float sa0 = accA.x + accA.y, sa1 = accB.x + accB.y;
;                 sa0 += dpp_f<0xB1>(sa0); sa1 += dpp_f<0xB1>(sa1);
;                 sa0 += dpp_f<0x4E>(sa0); sa1 += dpp_f<0x4E>(sa1);
;                 sa0 += dpp_f<0x141>(sa0); sa1 += dpp_f<0x141>(sa1);
;                 const f32x2 saA = {sa0, sa0}, saB = {sa1, sa1}, vA = {v01.x, v01.x}, vB = {v01.y, v01.y};
;                 f32x2 yA, yB;
; #pragma unroll
;                 for (int j = 0; j < 4; ++j) {
;                     f32x2 tA = vA * m2[j], tB = vB * m2[j];
;                     tA = saA * b2[j] + tA; tB = saB * b2[j] + tB;
;                     s[0][j] = s[0][j] * w2[j] + tA; s[1][j] = s[1][j] * w2[j] + tB;
	v_pk_mul_f32 v[20:21], v[2:3], v[64:65] op_sel_hi:[1,0]
	ds_read_b128 v[110:113], v180 offset:4864
	ds_read_b128 v[114:117], v180 offset:4880
	v_pk_fma_f32 v[20:21], v[4:5], v[64:65], v[20:21] op_sel:[0,1,0]
	ds_read_b64 v[150:151], v181 offset:21248
	ds_read_b128 v[134:137], v180 offset:13056
	v_pk_fma_f32 v[20:21], v[6:7], v[66:67], v[20:21] op_sel_hi:[1,0,1]
	ds_read_b128 v[138:141], v180 offset:13072
	ds_read_b128 v[118:121], v180 offset:768
	v_pk_fma_f32 v[20:21], v[8:9], v[66:67], v[20:21] op_sel:[0,1,0]
	ds_read_b128 v[122:125], v180 offset:784
	ds_read_b128 v[126:129], v180 offset:8960
	v_pk_fma_f32 v[20:21], v[10:11], v[68:69], v[20:21] op_sel_hi:[1,0,1]
	ds_read_b128 v[130:133], v180 offset:8976
	ds_read_b128 v[142:145], v180 offset:17152
	v_pk_fma_f32 v[20:21], v[12:13], v[68:69], v[20:21] op_sel:[0,1,0]
	ds_read_b128 v[146:149], v180 offset:17168
	v_add_f32_dpp v42, v42, v42 quad_perm:[1,0,3,2] row_mask:0xf bank_mask:0xf bound_ctrl:1
	v_pk_fma_f32 v[20:21], v[14:15], v[70:71], v[20:21] op_sel_hi:[1,0,1]
	v_add_f32_dpp v43, v43, v43 quad_perm:[1,0,3,2] row_mask:0xf bank_mask:0xf bound_ctrl:1
	v_add_f32_dpp v42, v42, v42 quad_perm:[2,3,0,1] row_mask:0xf bank_mask:0xf bound_ctrl:1
	v_pk_fma_f32 v[20:21], v[16:17], v[70:71], v[20:21] op_sel:[0,1,0]
	v_add_f32_dpp v43, v43, v43 quad_perm:[2,3,0,1] row_mask:0xf bank_mask:0xf bound_ctrl:1
	v_add_f32_dpp v42, v42, v42 row_half_mirror row_mask:0xf bank_mask:0xf bound_ctrl:1
	v_add_f32_dpp v20, v20, v20 quad_perm:[1,0,3,2] row_mask:0xf bank_mask:0xf bound_ctrl:1
	v_add_f32_dpp v21, v21, v21 quad_perm:[1,0,3,2] row_mask:0xf bank_mask:0xf bound_ctrl:1
	v_add_f32_dpp v43, v43, v43 row_half_mirror row_mask:0xf bank_mask:0xf bound_ctrl:1
	v_add_f32_dpp v20, v20, v20 quad_perm:[2,3,0,1] row_mask:0xf bank_mask:0xf bound_ctrl:1
	v_add_f32_dpp v21, v21, v21 quad_perm:[2,3,0,1] row_mask:0xf bank_mask:0xf bound_ctrl:1
	ds_write_b64 v184, v[42:43] offset:28928
	v_add_f32_dpp v20, v20, v20 row_half_mirror row_mask:0xf bank_mask:0xf bound_ctrl:1
	v_add_f32_dpp v21, v21, v21 row_half_mirror row_mask:0xf bank_mask:0xf bound_ctrl:1
	v_pk_mul_f32 v[24:25], v[104:105], v[88:89] op_sel_hi:[1,0]
	v_pk_mul_f32 v[26:27], v[104:105], v[88:89] op_sel:[0,1]
	v_pk_mul_f32 v[28:29], v[104:105], v[90:91] op_sel_hi:[1,0]
	v_pk_fma_f32 v[24:25], v[2:3], v[72:73], v[24:25] op_sel_hi:[1,0,1]
	v_pk_fma_f32 v[26:27], v[4:5], v[72:73], v[26:27] op_sel:[0,1,0]
	v_pk_fma_f32 v[28:29], v[6:7], v[74:75], v[28:29] op_sel_hi:[1,0,1]
	v_pk_fma_f32 v[2:3], v[20:21], v[80:81], v[24:25] op_sel_hi:[1,0,1]
	v_pk_fma_f32 v[4:5], v[20:21], v[80:81], v[26:27] op_sel:[0,1,0]
	v_pk_fma_f32 v[6:7], v[20:21], v[82:83], v[28:29] op_sel_hi:[1,0,1]
	v_pk_mul_f32 v[30:31], v[104:105], v[90:91] op_sel:[0,1]
	v_pk_mul_f32 v[32:33], v[104:105], v[92:93] op_sel_hi:[1,0]
	v_pk_mul_f32 v[34:35], v[104:105], v[92:93] op_sel:[0,1]
	v_pk_fma_f32 v[30:31], v[8:9], v[74:75], v[30:31] op_sel:[0,1,0]
	v_pk_fma_f32 v[32:33], v[10:11], v[76:77], v[32:33] op_sel_hi:[1,0,1]
	v_pk_fma_f32 v[34:35], v[12:13], v[76:77], v[34:35] op_sel:[0,1,0]
	v_pk_fma_f32 v[8:9], v[20:21], v[82:83], v[30:31] op_sel:[0,1,0]
	v_pk_fma_f32 v[10:11], v[20:21], v[84:85], v[32:33] op_sel_hi:[1,0,1]
	v_pk_fma_f32 v[12:13], v[20:21], v[84:85], v[34:35] op_sel:[0,1,0]
	v_pk_mul_f32 v[36:37], v[104:105], v[94:95] op_sel_hi:[1,0]
	v_pk_mul_f32 v[38:39], v[104:105], v[94:95] op_sel:[0,1]
	v_pk_mul_f32 v[40:41], v[2:3], v[96:97] op_sel_hi:[1,0]
	v_pk_fma_f32 v[36:37], v[14:15], v[78:79], v[36:37] op_sel_hi:[1,0,1]
	v_pk_fma_f32 v[38:39], v[16:17], v[78:79], v[38:39] op_sel:[0,1,0]
	v_pk_fma_f32 v[40:41], v[4:5], v[96:97], v[40:41] op_sel:[0,1,0]
	v_pk_fma_f32 v[14:15], v[20:21], v[86:87], v[36:37] op_sel_hi:[1,0,1]
	v_pk_fma_f32 v[16:17], v[20:21], v[86:87], v[38:39] op_sel:[0,1,0]
	v_pk_fma_f32 v[40:41], v[6:7], v[98:99], v[40:41] op_sel_hi:[1,0,1]
	v_pk_fma_f32 v[40:41], v[8:9], v[98:99], v[40:41] op_sel:[0,1,0]
	v_pk_fma_f32 v[40:41], v[10:11], v[100:101], v[40:41] op_sel_hi:[1,0,1]
	v_pk_fma_f32 v[40:41], v[12:13], v[100:101], v[40:41] op_sel:[0,1,0]
	v_pk_fma_f32 v[40:41], v[14:15], v[102:103], v[40:41] op_sel_hi:[1,0,1]
	v_pk_fma_f32 v[40:41], v[16:17], v[102:103], v[40:41] op_sel:[0,1,0]
	s_waitcnt lgkmcnt(0)
; __device__ __forceinline__ void rwkv_block(KP p, int o, int b, int hd, LAS unsigned char* lds, const bf16_t* P, bf16_t* YB) {
;     ...
;             for (int tt = 0; tt < 16; ++tt) {
;                 const int o8 = tt * 64 + c * 8;
;                 const f32x4 ka = *(const LAS f32x4*)(KK + o8), kb = *(const LAS f32x4*)(KK + o8 + 4);
;                 const f32x4 wa = *(const LAS f32x4*)(Wd + o8), wb = *(const LAS f32x4*)(Wd + o8 + 4);
;                 const f32x4 ba = *(const LAS f32x4*)(BB + o8), bb = *(const LAS f32x4*)(BB + o8 + 4);
;                 const f32x4 ma = *(const LAS f32x4*)(KM + o8), mb = *(const LAS f32x4*)(KM + o8 + 4);
;                 const f32x4 ra = *(const LAS f32x4*)(Rr + o8), rb = *(const LAS f32x4*)(Rr + o8 + 4);
;                 const f32x2 v01 = *(const LAS f32x2*)(Vv + tt * 64 + 2 * rp);
;                 const f32x2 k2[4] = {{ka[0], ka[1]}, {ka[2], ka[3]}, {kb[0], kb[1]}, {kb[2], kb[3]}};
;                 const f32x2 w2[4] = {{wa[0], wa[1]}, {wa[2], wa[3]}, {wb[0], wb[1]}, {wb[2], wb[3]}};
;                 const f32x2 b2[4] = {{ba[0], ba[1]}, {ba[2], ba[3]}, {bb[0], bb[1]}, {bb[2], bb[3]}};
;                 const f32x2 m2[4] = {{ma[0], ma[1]}, {ma[2], ma[3]}, {mb[0], mb[1]}, {mb[2], mb[3]}};
;                 const f32x2 r2[4] = {{ra[0], ra[1]}, {ra[2], ra[3]}, {rb[0], rb[1]}, {rb[2], rb[3]}};
;                 f32x2 accA = s[0][0] * k2[0], accB = s[1][0] * k2[0], accA2 = s[0][2] * k2[2], accB2 = s[1][2] * k2[2];
;                 accA = s[0][1] * k2[1] + accA; accB = s[1][1] * k2[1] + accB; accA2 = s[0][3] * k2[3] + accA2; accB2 = s[1][3] * k2[3] + accB2;
;                 accA = accA + accA2; accB = accB + accB2;
;                 float sa0 = accA.x + accA.y, sa1 = accB.x + accB.y;
;                 sa0 += dpp_f<0xB1>(sa0); sa1 += dpp_f<0xB1>(sa1);
;                 sa0 += dpp_f<0x4E>(sa0); sa1 += dpp_f<0x4E>(sa1);
;                 sa0 += dpp_f<0x141>(sa0); sa1 += dpp_f<0x141>(sa1);
;                 const f32x2 saA = {sa0, sa0}, saB = {sa1, sa1}, vA = {v01.x, v01.x}, vB = {v01.y, v01.y};
;                 f32x2 yA, yB;
; #pragma unroll
;                 for (int j = 0; j < 4; ++j) {
;                     f32x2 tA = vA * m2[j], tB = vB * m2[j];
;                     tA = saA * b2[j] + tA; tB = saB * b2[j] + tB;
;                     s[0][j] = s[0][j] * w2[j] + tA; s[1][j] = s[1][j] * w2[j] + tB;
	v_pk_mul_f32 v[20:21], v[2:3], v[110:111] op_sel_hi:[1,0]
	ds_read_b128 v[64:67], v180 offset:5120
	ds_read_b128 v[68:71], v180 offset:5136
	v_pk_fma_f32 v[20:21], v[4:5], v[110:111], v[20:21] op_sel:[0,1,0]
	ds_read_b64 v[104:105], v181 offset:21504
	ds_read_b128 v[88:91], v180 offset:13312
	v_pk_fma_f32 v[20:21], v[6:7], v[112:113], v[20:21] op_sel_hi:[1,0,1]
	ds_read_b128 v[92:95], v180 offset:13328
	ds_read_b128 v[72:75], v180 offset:1024
	v_pk_fma_f32 v[20:21], v[8:9], v[112:113], v[20:21] op_sel:[0,1,0]
	ds_read_b128 v[76:79], v180 offset:1040
	ds_read_b128 v[80:83], v180 offset:9216
	v_pk_fma_f32 v[20:21], v[10:11], v[114:115], v[20:21] op_sel_hi:[1,0,1]
	ds_read_b128 v[84:87], v180 offset:9232
	ds_read_b128 v[96:99], v180 offset:17408
	v_pk_fma_f32 v[20:21], v[12:13], v[114:115], v[20:21] op_sel:[0,1,0]
	ds_read_b128 v[100:103], v180 offset:17424
	v_add_f32_dpp v40, v40, v40 quad_perm:[1,0,3,2] row_mask:0xf bank_mask:0xf bound_ctrl:1
	v_pk_fma_f32 v[20:21], v[14:15], v[116:117], v[20:21] op_sel_hi:[1,0,1]
	v_add_f32_dpp v41, v41, v41 quad_perm:[1,0,3,2] row_mask:0xf bank_mask:0xf bound_ctrl:1
	v_add_f32_dpp v40, v40, v40 quad_perm:[2,3,0,1] row_mask:0xf bank_mask:0xf bound_ctrl:1
	v_pk_fma_f32 v[20:21], v[16:17], v[116:117], v[20:21] op_sel:[0,1,0]
	v_add_f32_dpp v41, v41, v41 quad_perm:[2,3,0,1] row_mask:0xf bank_mask:0xf bound_ctrl:1
	v_add_f32_dpp v40, v40, v40 row_half_mirror row_mask:0xf bank_mask:0xf bound_ctrl:1
	v_add_f32_dpp v20, v20, v20 quad_perm:[1,0,3,2] row_mask:0xf bank_mask:0xf bound_ctrl:1
	v_add_f32_dpp v21, v21, v21 quad_perm:[1,0,3,2] row_mask:0xf bank_mask:0xf bound_ctrl:1
	v_add_f32_dpp v41, v41, v41 row_half_mirror row_mask:0xf bank_mask:0xf bound_ctrl:1
	v_add_f32_dpp v20, v20, v20 quad_perm:[2,3,0,1] row_mask:0xf bank_mask:0xf bound_ctrl:1
	v_add_f32_dpp v21, v21, v21 quad_perm:[2,3,0,1] row_mask:0xf bank_mask:0xf bound_ctrl:1
	ds_write_b64 v184, v[40:41] offset:29184
	v_add_f32_dpp v20, v20, v20 row_half_mirror row_mask:0xf bank_mask:0xf bound_ctrl:1
	v_add_f32_dpp v21, v21, v21 row_half_mirror row_mask:0xf bank_mask:0xf bound_ctrl:1
	v_pk_mul_f32 v[24:25], v[150:151], v[134:135] op_sel_hi:[1,0]
	v_pk_mul_f32 v[26:27], v[150:151], v[134:135] op_sel:[0,1]
	v_pk_mul_f32 v[28:29], v[150:151], v[136:137] op_sel_hi:[1,0]
	v_pk_fma_f32 v[24:25], v[2:3], v[118:119], v[24:25] op_sel_hi:[1,0,1]
	v_pk_fma_f32 v[26:27], v[4:5], v[118:119], v[26:27] op_sel:[0,1,0]
	v_pk_fma_f32 v[28:29], v[6:7], v[120:121], v[28:29] op_sel_hi:[1,0,1]
	v_pk_fma_f32 v[2:3], v[20:21], v[126:127], v[24:25] op_sel_hi:[1,0,1]
	v_pk_fma_f32 v[4:5], v[20:21], v[126:127], v[26:27] op_sel:[0,1,0]
	v_pk_fma_f32 v[6:7], v[20:21], v[128:129], v[28:29] op_sel_hi:[1,0,1]
	v_pk_mul_f32 v[30:31], v[150:151], v[136:137] op_sel:[0,1]
	v_pk_mul_f32 v[32:33], v[150:151], v[138:139] op_sel_hi:[1,0]
	v_pk_mul_f32 v[34:35], v[150:151], v[138:139] op_sel:[0,1]
	v_pk_fma_f32 v[30:31], v[8:9], v[120:121], v[30:31] op_sel:[0,1,0]
	v_pk_fma_f32 v[32:33], v[10:11], v[122:123], v[32:33] op_sel_hi:[1,0,1]
	v_pk_fma_f32 v[34:35], v[12:13], v[122:123], v[34:35] op_sel:[0,1,0]
	v_pk_fma_f32 v[8:9], v[20:21], v[128:129], v[30:31] op_sel:[0,1,0]
	v_pk_fma_f32 v[10:11], v[20:21], v[130:131], v[32:33] op_sel_hi:[1,0,1]
	v_pk_fma_f32 v[12:13], v[20:21], v[130:131], v[34:35] op_sel:[0,1,0]
	v_pk_mul_f32 v[36:37], v[150:151], v[140:141] op_sel_hi:[1,0]
	v_pk_mul_f32 v[38:39], v[150:151], v[140:141] op_sel:[0,1]
	v_pk_mul_f32 v[42:43], v[2:3], v[142:143] op_sel_hi:[1,0]
	v_pk_fma_f32 v[36:37], v[14:15], v[124:125], v[36:37] op_sel_hi:[1,0,1]
	v_pk_fma_f32 v[38:39], v[16:17], v[124:125], v[38:39] op_sel:[0,1,0]
	v_pk_fma_f32 v[42:43], v[4:5], v[142:143], v[42:43] op_sel:[0,1,0]
	v_pk_fma_f32 v[14:15], v[20:21], v[132:133], v[36:37] op_sel_hi:[1,0,1]
	v_pk_fma_f32 v[16:17], v[20:21], v[132:133], v[38:39] op_sel:[0,1,0]
	v_pk_fma_f32 v[42:43], v[6:7], v[144:145], v[42:43] op_sel_hi:[1,0,1]
	v_pk_fma_f32 v[42:43], v[8:9], v[144:145], v[42:43] op_sel:[0,1,0]
	v_pk_fma_f32 v[42:43], v[10:11], v[146:147], v[42:43] op_sel_hi:[1,0,1]
	v_pk_fma_f32 v[42:43], v[12:13], v[146:147], v[42:43] op_sel:[0,1,0]
	v_pk_fma_f32 v[42:43], v[14:15], v[148:149], v[42:43] op_sel_hi:[1,0,1]
	v_pk_fma_f32 v[42:43], v[16:17], v[148:149], v[42:43] op_sel:[0,1,0]
	s_waitcnt lgkmcnt(0)
; __device__ __forceinline__ void rwkv_block(KP p, int o, int b, int hd, LAS unsigned char* lds, const bf16_t* P, bf16_t* YB) {
;     ...
;             for (int tt = 0; tt < 16; ++tt) {
;                 const int o8 = tt * 64 + c * 8;
;                 const f32x4 ka = *(const LAS f32x4*)(KK + o8), kb = *(const LAS f32x4*)(KK + o8 + 4);
;                 const f32x4 wa = *(const LAS f32x4*)(Wd + o8), wb = *(const LAS f32x4*)(Wd + o8 + 4);
;                 const f32x4 ba = *(const LAS f32x4*)(BB + o8), bb = *(const LAS f32x4*)(BB + o8 + 4);
;                 const f32x4 ma = *(const LAS f32x4*)(KM + o8), mb = *(const LAS f32x4*)(KM + o8 + 4);
;                 const f32x4 ra = *(const LAS f32x4*)(Rr + o8), rb = *(const LAS f32x4*)(Rr + o8 + 4);
;                 const f32x2 v01 = *(const LAS f32x2*)(Vv + tt * 64 + 2 * rp);
;                 const f32x2 k2[4] = {{ka[0], ka[1]}, {ka[2], ka[3]}, {kb[0], kb[1]}, {kb[2], kb[3]}};
;                 const f32x2 w2[4] = {{wa[0], wa[1]}, {wa[2], wa[3]}, {wb[0], wb[1]}, {wb[2], wb[3]}};
;                 const f32x2 b2[4] = {{ba[0], ba[1]}, {ba[2], ba[3]}, {bb[0], bb[1]}, {bb[2], bb[3]}};
;                 const f32x2 m2[4] = {{ma[0], ma[1]}, {ma[2], ma[3]}, {mb[0], mb[1]}, {mb[2], mb[3]}};
;                 const f32x2 r2[4] = {{ra[0], ra[1]}, {ra[2], ra[3]}, {rb[0], rb[1]}, {rb[2], rb[3]}};
;                 f32x2 accA = s[0][0] * k2[0], accB = s[1][0] * k2[0], accA2 = s[0][2] * k2[2], accB2 = s[1][2] * k2[2];
;                 accA = s[0][1] * k2[1] + accA; accB = s[1][1] * k2[1] + accB; accA2 = s[0][3] * k2[3] + accA2; accB2 = s[1][3] * k2[3] + accB2;
;                 accA = accA + accA2; accB = accB + accB2;
;                 float sa0 = accA.x + accA.y, sa1 = accB.x + accB.y;
;                 sa0 += dpp_f<0xB1>(sa0); sa1 += dpp_f<0xB1>(sa1);
;                 sa0 += dpp_f<0x4E>(sa0); sa1 += dpp_f<0x4E>(sa1);
;                 sa0 += dpp_f<0x141>(sa0); sa1 += dpp_f<0x141>(sa1);
;                 const f32x2 saA = {sa0, sa0}, saB = {sa1, sa1}, vA = {v01.x, v01.x}, vB = {v01.y, v01.y};
;                 f32x2 yA, yB;
; #pragma unroll
;                 for (int j = 0; j < 4; ++j) {
;                     f32x2 tA = vA * m2[j], tB = vB * m2[j];
;                     tA = saA * b2[j] + tA; tB = saB * b2[j] + tB;
;                     s[0][j] = s[0][j] * w2[j] + tA; s[1][j] = s[1][j] * w2[j] + tB;
	v_pk_mul_f32 v[20:21], v[2:3], v[64:65] op_sel_hi:[1,0]
	ds_read_b128 v[110:113], v180 offset:5376
	ds_read_b128 v[114:117], v180 offset:5392
	v_pk_fma_f32 v[20:21], v[4:5], v[64:65], v[20:21] op_sel:[0,1,0]
	ds_read_b64 v[150:151], v181 offset:21760
	ds_read_b128 v[134:137], v180 offset:13568
	v_pk_fma_f32 v[20:21], v[6:7], v[66:67], v[20:21] op_sel_hi:[1,0,1]
	ds_read_b128 v[138:141], v180 offset:13584
	ds_read_b128 v[118:121], v180 offset:1280
	v_pk_fma_f32 v[20:21], v[8:9], v[66:67], v[20:21] op_sel:[0,1,0]
	ds_read_b128 v[122:125], v180 offset:1296
	ds_read_b128 v[126:129], v180 offset:9472
	v_pk_fma_f32 v[20:21], v[10:11], v[68:69], v[20:21] op_sel_hi:[1,0,1]
	ds_read_b128 v[130:133], v180 offset:9488
	ds_read_b128 v[142:145], v180 offset:17664
	v_pk_fma_f32 v[20:21], v[12:13], v[68:69], v[20:21] op_sel:[0,1,0]
	ds_read_b128 v[146:149], v180 offset:17680
	v_add_f32_dpp v42, v42, v42 quad_perm:[1,0,3,2] row_mask:0xf bank_mask:0xf bound_ctrl:1
	v_pk_fma_f32 v[20:21], v[14:15], v[70:71], v[20:21] op_sel_hi:[1,0,1]
	v_add_f32_dpp v43, v43, v43 quad_perm:[1,0,3,2] row_mask:0xf bank_mask:0xf bound_ctrl:1
	v_add_f32_dpp v42, v42, v42 quad_perm:[2,3,0,1] row_mask:0xf bank_mask:0xf bound_ctrl:1
	v_pk_fma_f32 v[20:21], v[16:17], v[70:71], v[20:21] op_sel:[0,1,0]
	v_add_f32_dpp v43, v43, v43 quad_perm:[2,3,0,1] row_mask:0xf bank_mask:0xf bound_ctrl:1
	v_add_f32_dpp v42, v42, v42 row_half_mirror row_mask:0xf bank_mask:0xf bound_ctrl:1
	v_add_f32_dpp v20, v20, v20 quad_perm:[1,0,3,2] row_mask:0xf bank_mask:0xf bound_ctrl:1
	v_add_f32_dpp v21, v21, v21 quad_perm:[1,0,3,2] row_mask:0xf bank_mask:0xf bound_ctrl:1
	v_add_f32_dpp v43, v43, v43 row_half_mirror row_mask:0xf bank_mask:0xf bound_ctrl:1
	v_add_f32_dpp v20, v20, v20 quad_perm:[2,3,0,1] row_mask:0xf bank_mask:0xf bound_ctrl:1
	v_add_f32_dpp v21, v21, v21 quad_perm:[2,3,0,1] row_mask:0xf bank_mask:0xf bound_ctrl:1
	ds_write_b64 v184, v[42:43] offset:29440
	v_add_f32_dpp v20, v20, v20 row_half_mirror row_mask:0xf bank_mask:0xf bound_ctrl:1
	v_add_f32_dpp v21, v21, v21 row_half_mirror row_mask:0xf bank_mask:0xf bound_ctrl:1
	v_pk_mul_f32 v[24:25], v[104:105], v[88:89] op_sel_hi:[1,0]
	v_pk_mul_f32 v[26:27], v[104:105], v[88:89] op_sel:[0,1]
	v_pk_mul_f32 v[28:29], v[104:105], v[90:91] op_sel_hi:[1,0]
	v_pk_fma_f32 v[24:25], v[2:3], v[72:73], v[24:25] op_sel_hi:[1,0,1]
	v_pk_fma_f32 v[26:27], v[4:5], v[72:73], v[26:27] op_sel:[0,1,0]
	v_pk_fma_f32 v[28:29], v[6:7], v[74:75], v[28:29] op_sel_hi:[1,0,1]
	v_pk_fma_f32 v[2:3], v[20:21], v[80:81], v[24:25] op_sel_hi:[1,0,1]
	v_pk_fma_f32 v[4:5], v[20:21], v[80:81], v[26:27] op_sel:[0,1,0]
	v_pk_fma_f32 v[6:7], v[20:21], v[82:83], v[28:29] op_sel_hi:[1,0,1]
	v_pk_mul_f32 v[30:31], v[104:105], v[90:91] op_sel:[0,1]
	v_pk_mul_f32 v[32:33], v[104:105], v[92:93] op_sel_hi:[1,0]
	v_pk_mul_f32 v[34:35], v[104:105], v[92:93] op_sel:[0,1]
	v_pk_fma_f32 v[30:31], v[8:9], v[74:75], v[30:31] op_sel:[0,1,0]
	v_pk_fma_f32 v[32:33], v[10:11], v[76:77], v[32:33] op_sel_hi:[1,0,1]
	v_pk_fma_f32 v[34:35], v[12:13], v[76:77], v[34:35] op_sel:[0,1,0]
	v_pk_fma_f32 v[8:9], v[20:21], v[82:83], v[30:31] op_sel:[0,1,0]
	v_pk_fma_f32 v[10:11], v[20:21], v[84:85], v[32:33] op_sel_hi:[1,0,1]
	v_pk_fma_f32 v[12:13], v[20:21], v[84:85], v[34:35] op_sel:[0,1,0]
	v_pk_mul_f32 v[36:37], v[104:105], v[94:95] op_sel_hi:[1,0]
	v_pk_mul_f32 v[38:39], v[104:105], v[94:95] op_sel:[0,1]
	v_pk_mul_f32 v[40:41], v[2:3], v[96:97] op_sel_hi:[1,0]
	v_pk_fma_f32 v[36:37], v[14:15], v[78:79], v[36:37] op_sel_hi:[1,0,1]
	v_pk_fma_f32 v[38:39], v[16:17], v[78:79], v[38:39] op_sel:[0,1,0]
	v_pk_fma_f32 v[40:41], v[4:5], v[96:97], v[40:41] op_sel:[0,1,0]
	v_pk_fma_f32 v[14:15], v[20:21], v[86:87], v[36:37] op_sel_hi:[1,0,1]
	v_pk_fma_f32 v[16:17], v[20:21], v[86:87], v[38:39] op_sel:[0,1,0]
	v_pk_fma_f32 v[40:41], v[6:7], v[98:99], v[40:41] op_sel_hi:[1,0,1]
	v_pk_fma_f32 v[40:41], v[8:9], v[98:99], v[40:41] op_sel:[0,1,0]
	v_pk_fma_f32 v[40:41], v[10:11], v[100:101], v[40:41] op_sel_hi:[1,0,1]
	v_pk_fma_f32 v[40:41], v[12:13], v[100:101], v[40:41] op_sel:[0,1,0]
	v_pk_fma_f32 v[40:41], v[14:15], v[102:103], v[40:41] op_sel_hi:[1,0,1]
	v_pk_fma_f32 v[40:41], v[16:17], v[102:103], v[40:41] op_sel:[0,1,0]
	s_waitcnt lgkmcnt(0)
; __device__ __forceinline__ void rwkv_block(KP p, int o, int b, int hd, LAS unsigned char* lds, const bf16_t* P, bf16_t* YB) {
;     ...
;             for (int tt = 0; tt < 16; ++tt) {
;                 const int o8 = tt * 64 + c * 8;
;                 const f32x4 ka = *(const LAS f32x4*)(KK + o8), kb = *(const LAS f32x4*)(KK + o8 + 4);
;                 const f32x4 wa = *(const LAS f32x4*)(Wd + o8), wb = *(const LAS f32x4*)(Wd + o8 + 4);
;                 const f32x4 ba = *(const LAS f32x4*)(BB + o8), bb = *(const LAS f32x4*)(BB + o8 + 4);
;                 const f32x4 ma = *(const LAS f32x4*)(KM + o8), mb = *(const LAS f32x4*)(KM + o8 + 4);
;                 const f32x4 ra = *(const LAS f32x4*)(Rr + o8), rb = *(const LAS f32x4*)(Rr + o8 + 4);
;                 const f32x2 v01 = *(const LAS f32x2*)(Vv + tt * 64 + 2 * rp);
;                 const f32x2 k2[4] = {{ka[0], ka[1]}, {ka[2], ka[3]}, {kb[0], kb[1]}, {kb[2], kb[3]}};
;                 const f32x2 w2[4] = {{wa[0], wa[1]}, {wa[2], wa[3]}, {wb[0], wb[1]}, {wb[2], wb[3]}};
;                 const f32x2 b2[4] = {{ba[0], ba[1]}, {ba[2], ba[3]}, {bb[0], bb[1]}, {bb[2], bb[3]}};
;                 const f32x2 m2[4] = {{ma[0], ma[1]}, {ma[2], ma[3]}, {mb[0], mb[1]}, {mb[2], mb[3]}};
;                 const f32x2 r2[4] = {{ra[0], ra[1]}, {ra[2], ra[3]}, {rb[0], rb[1]}, {rb[2], rb[3]}};
;                 f32x2 accA = s[0][0] * k2[0], accB = s[1][0] * k2[0], accA2 = s[0][2] * k2[2], accB2 = s[1][2] * k2[2];
;                 accA = s[0][1] * k2[1] + accA; accB = s[1][1] * k2[1] + accB; accA2 = s[0][3] * k2[3] + accA2; accB2 = s[1][3] * k2[3] + accB2;
;                 accA = accA + accA2; accB = accB + accB2;
;                 float sa0 = accA.x + accA.y, sa1 = accB.x + accB.y;
;                 sa0 += dpp_f<0xB1>(sa0); sa1 += dpp_f<0xB1>(sa1);
;                 sa0 += dpp_f<0x4E>(sa0); sa1 += dpp_f<0x4E>(sa1);
;                 sa0 += dpp_f<0x141>(sa0); sa1 += dpp_f<0x141>(sa1);
;                 const f32x2 saA = {sa0, sa0}, saB = {sa1, sa1}, vA = {v01.x, v01.x}, vB = {v01.y, v01.y};
;                 f32x2 yA, yB;
; #pragma unroll
;                 for (int j = 0; j < 4; ++j) {
;                     f32x2 tA = vA * m2[j], tB = vB * m2[j];
;                     tA = saA * b2[j] + tA; tB = saB * b2[j] + tB;
;                     s[0][j] = s[0][j] * w2[j] + tA; s[1][j] = s[1][j] * w2[j] + tB;
	v_pk_mul_f32 v[20:21], v[2:3], v[110:111] op_sel_hi:[1,0]
	ds_read_b128 v[64:67], v180 offset:5632
	ds_read_b128 v[68:71], v180 offset:5648
	v_pk_fma_f32 v[20:21], v[4:5], v[110:111], v[20:21] op_sel:[0,1,0]
	ds_read_b64 v[104:105], v181 offset:22016
	ds_read_b128 v[88:91], v180 offset:13824
	v_pk_fma_f32 v[20:21], v[6:7], v[112:113], v[20:21] op_sel_hi:[1,0,1]
	ds_read_b128 v[92:95], v180 offset:13840
	ds_read_b128 v[72:75], v180 offset:1536
	v_pk_fma_f32 v[20:21], v[8:9], v[112:113], v[20:21] op_sel:[0,1,0]
	ds_read_b128 v[76:79], v180 offset:1552
	ds_read_b128 v[80:83], v180 offset:9728
	v_pk_fma_f32 v[20:21], v[10:11], v[114:115], v[20:21] op_sel_hi:[1,0,1]
	ds_read_b128 v[84:87], v180 offset:9744
	ds_read_b128 v[96:99], v180 offset:17920
	v_pk_fma_f32 v[20:21], v[12:13], v[114:115], v[20:21] op_sel:[0,1,0]
	ds_read_b128 v[100:103], v180 offset:17936
	v_add_f32_dpp v40, v40, v40 quad_perm:[1,0,3,2] row_mask:0xf bank_mask:0xf bound_ctrl:1
	v_pk_fma_f32 v[20:21], v[14:15], v[116:117], v[20:21] op_sel_hi:[1,0,1]
	v_add_f32_dpp v41, v41, v41 quad_perm:[1,0,3,2] row_mask:0xf bank_mask:0xf bound_ctrl:1
	v_add_f32_dpp v40, v40, v40 quad_perm:[2,3,0,1] row_mask:0xf bank_mask:0xf bound_ctrl:1
	v_pk_fma_f32 v[20:21], v[16:17], v[116:117], v[20:21] op_sel:[0,1,0]
	v_add_f32_dpp v41, v41, v41 quad_perm:[2,3,0,1] row_mask:0xf bank_mask:0xf bound_ctrl:1
	v_add_f32_dpp v40, v40, v40 row_half_mirror row_mask:0xf bank_mask:0xf bound_ctrl:1
	v_add_f32_dpp v20, v20, v20 quad_perm:[1,0,3,2] row_mask:0xf bank_mask:0xf bound_ctrl:1
	v_add_f32_dpp v21, v21, v21 quad_perm:[1,0,3,2] row_mask:0xf bank_mask:0xf bound_ctrl:1
	v_add_f32_dpp v41, v41, v41 row_half_mirror row_mask:0xf bank_mask:0xf bound_ctrl:1
	v_add_f32_dpp v20, v20, v20 quad_perm:[2,3,0,1] row_mask:0xf bank_mask:0xf bound_ctrl:1
	v_add_f32_dpp v21, v21, v21 quad_perm:[2,3,0,1] row_mask:0xf bank_mask:0xf bound_ctrl:1
	ds_write_b64 v184, v[40:41] offset:29696
	v_add_f32_dpp v20, v20, v20 row_half_mirror row_mask:0xf bank_mask:0xf bound_ctrl:1
	v_add_f32_dpp v21, v21, v21 row_half_mirror row_mask:0xf bank_mask:0xf bound_ctrl:1
	v_pk_mul_f32 v[24:25], v[150:151], v[134:135] op_sel_hi:[1,0]
	v_pk_mul_f32 v[26:27], v[150:151], v[134:135] op_sel:[0,1]
	v_pk_mul_f32 v[28:29], v[150:151], v[136:137] op_sel_hi:[1,0]
	v_pk_fma_f32 v[24:25], v[2:3], v[118:119], v[24:25] op_sel_hi:[1,0,1]
	v_pk_fma_f32 v[26:27], v[4:5], v[118:119], v[26:27] op_sel:[0,1,0]
	v_pk_fma_f32 v[28:29], v[6:7], v[120:121], v[28:29] op_sel_hi:[1,0,1]
	v_pk_fma_f32 v[2:3], v[20:21], v[126:127], v[24:25] op_sel_hi:[1,0,1]
	v_pk_fma_f32 v[4:5], v[20:21], v[126:127], v[26:27] op_sel:[0,1,0]
	v_pk_fma_f32 v[6:7], v[20:21], v[128:129], v[28:29] op_sel_hi:[1,0,1]
	v_pk_mul_f32 v[30:31], v[150:151], v[136:137] op_sel:[0,1]
	v_pk_mul_f32 v[32:33], v[150:151], v[138:139] op_sel_hi:[1,0]
	v_pk_mul_f32 v[34:35], v[150:151], v[138:139] op_sel:[0,1]
	v_pk_fma_f32 v[30:31], v[8:9], v[120:121], v[30:31] op_sel:[0,1,0]
	v_pk_fma_f32 v[32:33], v[10:11], v[122:123], v[32:33] op_sel_hi:[1,0,1]
	v_pk_fma_f32 v[34:35], v[12:13], v[122:123], v[34:35] op_sel:[0,1,0]
	v_pk_fma_f32 v[8:9], v[20:21], v[128:129], v[30:31] op_sel:[0,1,0]
	v_pk_fma_f32 v[10:11], v[20:21], v[130:131], v[32:33] op_sel_hi:[1,0,1]
	v_pk_fma_f32 v[12:13], v[20:21], v[130:131], v[34:35] op_sel:[0,1,0]
	v_pk_mul_f32 v[36:37], v[150:151], v[140:141] op_sel_hi:[1,0]
	v_pk_mul_f32 v[38:39], v[150:151], v[140:141] op_sel:[0,1]
	v_pk_mul_f32 v[42:43], v[2:3], v[142:143] op_sel_hi:[1,0]
	v_pk_fma_f32 v[36:37], v[14:15], v[124:125], v[36:37] op_sel_hi:[1,0,1]
	v_pk_fma_f32 v[38:39], v[16:17], v[124:125], v[38:39] op_sel:[0,1,0]
	v_pk_fma_f32 v[42:43], v[4:5], v[142:143], v[42:43] op_sel:[0,1,0]
	v_pk_fma_f32 v[14:15], v[20:21], v[132:133], v[36:37] op_sel_hi:[1,0,1]
	v_pk_fma_f32 v[16:17], v[20:21], v[132:133], v[38:39] op_sel:[0,1,0]
	v_pk_fma_f32 v[42:43], v[6:7], v[144:145], v[42:43] op_sel_hi:[1,0,1]
	v_pk_fma_f32 v[42:43], v[8:9], v[144:145], v[42:43] op_sel:[0,1,0]
	v_pk_fma_f32 v[42:43], v[10:11], v[146:147], v[42:43] op_sel_hi:[1,0,1]
	v_pk_fma_f32 v[42:43], v[12:13], v[146:147], v[42:43] op_sel:[0,1,0]
	v_pk_fma_f32 v[42:43], v[14:15], v[148:149], v[42:43] op_sel_hi:[1,0,1]
	v_pk_fma_f32 v[42:43], v[16:17], v[148:149], v[42:43] op_sel:[0,1,0]
	s_waitcnt lgkmcnt(0)
; __device__ __forceinline__ void rwkv_block(KP p, int o, int b, int hd, LAS unsigned char* lds, const bf16_t* P, bf16_t* YB) {
;     ...
;             for (int tt = 0; tt < 16; ++tt) {
;                 const int o8 = tt * 64 + c * 8;
;                 const f32x4 ka = *(const LAS f32x4*)(KK + o8), kb = *(const LAS f32x4*)(KK + o8 + 4);
;                 const f32x4 wa = *(const LAS f32x4*)(Wd + o8), wb = *(const LAS f32x4*)(Wd + o8 + 4);
;                 const f32x4 ba = *(const LAS f32x4*)(BB + o8), bb = *(const LAS f32x4*)(BB + o8 + 4);
;                 const f32x4 ma = *(const LAS f32x4*)(KM + o8), mb = *(const LAS f32x4*)(KM + o8 + 4);
;                 const f32x4 ra = *(const LAS f32x4*)(Rr + o8), rb = *(const LAS f32x4*)(Rr + o8 + 4);
;                 const f32x2 v01 = *(const LAS f32x2*)(Vv + tt * 64 + 2 * rp);
;                 const f32x2 k2[4] = {{ka[0], ka[1]}, {ka[2], ka[3]}, {kb[0], kb[1]}, {kb[2], kb[3]}};
;                 const f32x2 w2[4] = {{wa[0], wa[1]}, {wa[2], wa[3]}, {wb[0], wb[1]}, {wb[2], wb[3]}};
;                 const f32x2 b2[4] = {{ba[0], ba[1]}, {ba[2], ba[3]}, {bb[0], bb[1]}, {bb[2], bb[3]}};
;                 const f32x2 m2[4] = {{ma[0], ma[1]}, {ma[2], ma[3]}, {mb[0], mb[1]}, {mb[2], mb[3]}};
;                 const f32x2 r2[4] = {{ra[0], ra[1]}, {ra[2], ra[3]}, {rb[0], rb[1]}, {rb[2], rb[3]}};
;                 f32x2 accA = s[0][0] * k2[0], accB = s[1][0] * k2[0], accA2 = s[0][2] * k2[2], accB2 = s[1][2] * k2[2];
;                 accA = s[0][1] * k2[1] + accA; accB = s[1][1] * k2[1] + accB; accA2 = s[0][3] * k2[3] + accA2; accB2 = s[1][3] * k2[3] + accB2;
;                 accA = accA + accA2; accB = accB + accB2;
;                 float sa0 = accA.x + accA.y, sa1 = accB.x + accB.y;
;                 sa0 += dpp_f<0xB1>(sa0); sa1 += dpp_f<0xB1>(sa1);
;                 sa0 += dpp_f<0x4E>(sa0); sa1 += dpp_f<0x4E>(sa1);
;                 sa0 += dpp_f<0x141>(sa0); sa1 += dpp_f<0x141>(sa1);
;                 const f32x2 saA = {sa0, sa0}, saB = {sa1, sa1}, vA = {v01.x, v01.x}, vB = {v01.y, v01.y};
;                 f32x2 yA, yB;
; #pragma unroll
;                 for (int j = 0; j < 4; ++j) {
;                     f32x2 tA = vA * m2[j], tB = vB * m2[j];
;                     tA = saA * b2[j] + tA; tB = saB * b2[j] + tB;
;                     s[0][j] = s[0][j] * w2[j] + tA; s[1][j] = s[1][j] * w2[j] + tB;
	v_pk_mul_f32 v[20:21], v[2:3], v[64:65] op_sel_hi:[1,0]
	ds_read_b128 v[110:113], v180 offset:5888
	ds_read_b128 v[114:117], v180 offset:5904
	v_pk_fma_f32 v[20:21], v[4:5], v[64:65], v[20:21] op_sel:[0,1,0]
	ds_read_b64 v[150:151], v181 offset:22272
	ds_read_b128 v[134:137], v180 offset:14080
	v_pk_fma_f32 v[20:21], v[6:7], v[66:67], v[20:21] op_sel_hi:[1,0,1]
	ds_read_b128 v[138:141], v180 offset:14096
	ds_read_b128 v[118:121], v180 offset:1792
	v_pk_fma_f32 v[20:21], v[8:9], v[66:67], v[20:21] op_sel:[0,1,0]
	ds_read_b128 v[122:125], v180 offset:1808
	ds_read_b128 v[126:129], v180 offset:9984
	v_pk_fma_f32 v[20:21], v[10:11], v[68:69], v[20:21] op_sel_hi:[1,0,1]
	ds_read_b128 v[130:133], v180 offset:10000
	ds_read_b128 v[142:145], v180 offset:18176
	v_pk_fma_f32 v[20:21], v[12:13], v[68:69], v[20:21] op_sel:[0,1,0]
	ds_read_b128 v[146:149], v180 offset:18192
	v_add_f32_dpp v42, v42, v42 quad_perm:[1,0,3,2] row_mask:0xf bank_mask:0xf bound_ctrl:1
	v_pk_fma_f32 v[20:21], v[14:15], v[70:71], v[20:21] op_sel_hi:[1,0,1]
	v_add_f32_dpp v43, v43, v43 quad_perm:[1,0,3,2] row_mask:0xf bank_mask:0xf bound_ctrl:1
	v_add_f32_dpp v42, v42, v42 quad_perm:[2,3,0,1] row_mask:0xf bank_mask:0xf bound_ctrl:1
	v_pk_fma_f32 v[20:21], v[16:17], v[70:71], v[20:21] op_sel:[0,1,0]
	v_add_f32_dpp v43, v43, v43 quad_perm:[2,3,0,1] row_mask:0xf bank_mask:0xf bound_ctrl:1
	v_add_f32_dpp v42, v42, v42 row_half_mirror row_mask:0xf bank_mask:0xf bound_ctrl:1
	v_add_f32_dpp v20, v20, v20 quad_perm:[1,0,3,2] row_mask:0xf bank_mask:0xf bound_ctrl:1
	v_add_f32_dpp v21, v21, v21 quad_perm:[1,0,3,2] row_mask:0xf bank_mask:0xf bound_ctrl:1
	v_add_f32_dpp v43, v43, v43 row_half_mirror row_mask:0xf bank_mask:0xf bound_ctrl:1
	v_add_f32_dpp v20, v20, v20 quad_perm:[2,3,0,1] row_mask:0xf bank_mask:0xf bound_ctrl:1
	v_add_f32_dpp v21, v21, v21 quad_perm:[2,3,0,1] row_mask:0xf bank_mask:0xf bound_ctrl:1
	ds_write_b64 v184, v[42:43] offset:29952
	v_add_f32_dpp v20, v20, v20 row_half_mirror row_mask:0xf bank_mask:0xf bound_ctrl:1
	v_add_f32_dpp v21, v21, v21 row_half_mirror row_mask:0xf bank_mask:0xf bound_ctrl:1
	v_pk_mul_f32 v[24:25], v[104:105], v[88:89] op_sel_hi:[1,0]
	v_pk_mul_f32 v[26:27], v[104:105], v[88:89] op_sel:[0,1]
	v_pk_mul_f32 v[28:29], v[104:105], v[90:91] op_sel_hi:[1,0]
	v_pk_fma_f32 v[24:25], v[2:3], v[72:73], v[24:25] op_sel_hi:[1,0,1]
	v_pk_fma_f32 v[26:27], v[4:5], v[72:73], v[26:27] op_sel:[0,1,0]
	v_pk_fma_f32 v[28:29], v[6:7], v[74:75], v[28:29] op_sel_hi:[1,0,1]
	v_pk_fma_f32 v[2:3], v[20:21], v[80:81], v[24:25] op_sel_hi:[1,0,1]
	v_pk_fma_f32 v[4:5], v[20:21], v[80:81], v[26:27] op_sel:[0,1,0]
	v_pk_fma_f32 v[6:7], v[20:21], v[82:83], v[28:29] op_sel_hi:[1,0,1]
	v_pk_mul_f32 v[30:31], v[104:105], v[90:91] op_sel:[0,1]
	v_pk_mul_f32 v[32:33], v[104:105], v[92:93] op_sel_hi:[1,0]
	v_pk_mul_f32 v[34:35], v[104:105], v[92:93] op_sel:[0,1]
	v_pk_fma_f32 v[30:31], v[8:9], v[74:75], v[30:31] op_sel:[0,1,0]
	v_pk_fma_f32 v[32:33], v[10:11], v[76:77], v[32:33] op_sel_hi:[1,0,1]
	v_pk_fma_f32 v[34:35], v[12:13], v[76:77], v[34:35] op_sel:[0,1,0]
	v_pk_fma_f32 v[8:9], v[20:21], v[82:83], v[30:31] op_sel:[0,1,0]
	v_pk_fma_f32 v[10:11], v[20:21], v[84:85], v[32:33] op_sel_hi:[1,0,1]
	v_pk_fma_f32 v[12:13], v[20:21], v[84:85], v[34:35] op_sel:[0,1,0]
	v_pk_mul_f32 v[36:37], v[104:105], v[94:95] op_sel_hi:[1,0]
	v_pk_mul_f32 v[38:39], v[104:105], v[94:95] op_sel:[0,1]
	v_pk_mul_f32 v[40:41], v[2:3], v[96:97] op_sel_hi:[1,0]
	v_pk_fma_f32 v[36:37], v[14:15], v[78:79], v[36:37] op_sel_hi:[1,0,1]
	v_pk_fma_f32 v[38:39], v[16:17], v[78:79], v[38:39] op_sel:[0,1,0]
	v_pk_fma_f32 v[40:41], v[4:5], v[96:97], v[40:41] op_sel:[0,1,0]
	v_pk_fma_f32 v[14:15], v[20:21], v[86:87], v[36:37] op_sel_hi:[1,0,1]
	v_pk_fma_f32 v[16:17], v[20:21], v[86:87], v[38:39] op_sel:[0,1,0]
	v_pk_fma_f32 v[40:41], v[6:7], v[98:99], v[40:41] op_sel_hi:[1,0,1]
	v_pk_fma_f32 v[40:41], v[8:9], v[98:99], v[40:41] op_sel:[0,1,0]
	v_pk_fma_f32 v[40:41], v[10:11], v[100:101], v[40:41] op_sel_hi:[1,0,1]
	v_pk_fma_f32 v[40:41], v[12:13], v[100:101], v[40:41] op_sel:[0,1,0]
	v_pk_fma_f32 v[40:41], v[14:15], v[102:103], v[40:41] op_sel_hi:[1,0,1]
	v_pk_fma_f32 v[40:41], v[16:17], v[102:103], v[40:41] op_sel:[0,1,0]
	s_waitcnt lgkmcnt(0)
; __device__ __forceinline__ void rwkv_block(KP p, int o, int b, int hd, LAS unsigned char* lds, const bf16_t* P, bf16_t* YB) {
;     ...
;             for (int tt = 0; tt < 16; ++tt) {
;                 const int o8 = tt * 64 + c * 8;
;                 const f32x4 ka = *(const LAS f32x4*)(KK + o8), kb = *(const LAS f32x4*)(KK + o8 + 4);
;                 const f32x4 wa = *(const LAS f32x4*)(Wd + o8), wb = *(const LAS f32x4*)(Wd + o8 + 4);
;                 const f32x4 ba = *(const LAS f32x4*)(BB + o8), bb = *(const LAS f32x4*)(BB + o8 + 4);
;                 const f32x4 ma = *(const LAS f32x4*)(KM + o8), mb = *(const LAS f32x4*)(KM + o8 + 4);
;                 const f32x4 ra = *(const LAS f32x4*)(Rr + o8), rb = *(const LAS f32x4*)(Rr + o8 + 4);
;                 const f32x2 v01 = *(const LAS f32x2*)(Vv + tt * 64 + 2 * rp);
;                 const f32x2 k2[4] = {{ka[0], ka[1]}, {ka[2], ka[3]}, {kb[0], kb[1]}, {kb[2], kb[3]}};
;                 const f32x2 w2[4] = {{wa[0], wa[1]}, {wa[2], wa[3]}, {wb[0], wb[1]}, {wb[2], wb[3]}};
;                 const f32x2 b2[4] = {{ba[0], ba[1]}, {ba[2], ba[3]}, {bb[0], bb[1]}, {bb[2], bb[3]}};
;                 const f32x2 m2[4] = {{ma[0], ma[1]}, {ma[2], ma[3]}, {mb[0], mb[1]}, {mb[2], mb[3]}};
;                 const f32x2 r2[4] = {{ra[0], ra[1]}, {ra[2], ra[3]}, {rb[0], rb[1]}, {rb[2], rb[3]}};
;                 f32x2 accA = s[0][0] * k2[0], accB = s[1][0] * k2[0], accA2 = s[0][2] * k2[2], accB2 = s[1][2] * k2[2];
;                 accA = s[0][1] * k2[1] + accA; accB = s[1][1] * k2[1] + accB; accA2 = s[0][3] * k2[3] + accA2; accB2 = s[1][3] * k2[3] + accB2;
;                 accA = accA + accA2; accB = accB + accB2;
;                 float sa0 = accA.x + accA.y, sa1 = accB.x + accB.y;
;                 sa0 += dpp_f<0xB1>(sa0); sa1 += dpp_f<0xB1>(sa1);
;                 sa0 += dpp_f<0x4E>(sa0); sa1 += dpp_f<0x4E>(sa1);
;                 sa0 += dpp_f<0x141>(sa0); sa1 += dpp_f<0x141>(sa1);
;                 const f32x2 saA = {sa0, sa0}, saB = {sa1, sa1}, vA = {v01.x, v01.x}, vB = {v01.y, v01.y};
;                 f32x2 yA, yB;
; #pragma unroll
;                 for (int j = 0; j < 4; ++j) {
;                     f32x2 tA = vA * m2[j], tB = vB * m2[j];
;                     tA = saA * b2[j] + tA; tB = saB * b2[j] + tB;
;                     s[0][j] = s[0][j] * w2[j] + tA; s[1][j] = s[1][j] * w2[j] + tB;
	v_pk_mul_f32 v[20:21], v[2:3], v[110:111] op_sel_hi:[1,0]
	ds_read_b128 v[64:67], v180 offset:6144
	ds_read_b128 v[68:71], v180 offset:6160
	v_pk_fma_f32 v[20:21], v[4:5], v[110:111], v[20:21] op_sel:[0,1,0]
	ds_read_b64 v[104:105], v181 offset:22528
	ds_read_b128 v[88:91], v180 offset:14336
	v_pk_fma_f32 v[20:21], v[6:7], v[112:113], v[20:21] op_sel_hi:[1,0,1]
	ds_read_b128 v[92:95], v180 offset:14352
	ds_read_b128 v[72:75], v180 offset:2048
	v_pk_fma_f32 v[20:21], v[8:9], v[112:113], v[20:21] op_sel:[0,1,0]
	ds_read_b128 v[76:79], v180 offset:2064
	ds_read_b128 v[80:83], v180 offset:10240
	v_pk_fma_f32 v[20:21], v[10:11], v[114:115], v[20:21] op_sel_hi:[1,0,1]
	ds_read_b128 v[84:87], v180 offset:10256
	ds_read_b128 v[96:99], v180 offset:18432
	v_pk_fma_f32 v[20:21], v[12:13], v[114:115], v[20:21] op_sel:[0,1,0]
	ds_read_b128 v[100:103], v180 offset:18448
	v_add_f32_dpp v40, v40, v40 quad_perm:[1,0,3,2] row_mask:0xf bank_mask:0xf bound_ctrl:1
	v_pk_fma_f32 v[20:21], v[14:15], v[116:117], v[20:21] op_sel_hi:[1,0,1]
	v_add_f32_dpp v41, v41, v41 quad_perm:[1,0,3,2] row_mask:0xf bank_mask:0xf bound_ctrl:1
	v_add_f32_dpp v40, v40, v40 quad_perm:[2,3,0,1] row_mask:0xf bank_mask:0xf bound_ctrl:1
	v_pk_fma_f32 v[20:21], v[16:17], v[116:117], v[20:21] op_sel:[0,1,0]
	v_add_f32_dpp v41, v41, v41 quad_perm:[2,3,0,1] row_mask:0xf bank_mask:0xf bound_ctrl:1
	v_add_f32_dpp v40, v40, v40 row_half_mirror row_mask:0xf bank_mask:0xf bound_ctrl:1
	v_add_f32_dpp v20, v20, v20 quad_perm:[1,0,3,2] row_mask:0xf bank_mask:0xf bound_ctrl:1
	v_add_f32_dpp v21, v21, v21 quad_perm:[1,0,3,2] row_mask:0xf bank_mask:0xf bound_ctrl:1
	v_add_f32_dpp v41, v41, v41 row_half_mirror row_mask:0xf bank_mask:0xf bound_ctrl:1
	v_add_f32_dpp v20, v20, v20 quad_perm:[2,3,0,1] row_mask:0xf bank_mask:0xf bound_ctrl:1
	v_add_f32_dpp v21, v21, v21 quad_perm:[2,3,0,1] row_mask:0xf bank_mask:0xf bound_ctrl:1
	ds_write_b64 v184, v[40:41] offset:30208
	v_add_f32_dpp v20, v20, v20 row_half_mirror row_mask:0xf bank_mask:0xf bound_ctrl:1
	v_add_f32_dpp v21, v21, v21 row_half_mirror row_mask:0xf bank_mask:0xf bound_ctrl:1
	v_pk_mul_f32 v[24:25], v[150:151], v[134:135] op_sel_hi:[1,0]
	v_pk_mul_f32 v[26:27], v[150:151], v[134:135] op_sel:[0,1]
	v_pk_mul_f32 v[28:29], v[150:151], v[136:137] op_sel_hi:[1,0]
	v_pk_fma_f32 v[24:25], v[2:3], v[118:119], v[24:25] op_sel_hi:[1,0,1]
	v_pk_fma_f32 v[26:27], v[4:5], v[118:119], v[26:27] op_sel:[0,1,0]
	v_pk_fma_f32 v[28:29], v[6:7], v[120:121], v[28:29] op_sel_hi:[1,0,1]
	v_pk_fma_f32 v[2:3], v[20:21], v[126:127], v[24:25] op_sel_hi:[1,0,1]
	v_pk_fma_f32 v[4:5], v[20:21], v[126:127], v[26:27] op_sel:[0,1,0]
	v_pk_fma_f32 v[6:7], v[20:21], v[128:129], v[28:29] op_sel_hi:[1,0,1]
	v_pk_mul_f32 v[30:31], v[150:151], v[136:137] op_sel:[0,1]
	v_pk_mul_f32 v[32:33], v[150:151], v[138:139] op_sel_hi:[1,0]
	v_pk_mul_f32 v[34:35], v[150:151], v[138:139] op_sel:[0,1]
	v_pk_fma_f32 v[30:31], v[8:9], v[120:121], v[30:31] op_sel:[0,1,0]
	v_pk_fma_f32 v[32:33], v[10:11], v[122:123], v[32:33] op_sel_hi:[1,0,1]
	v_pk_fma_f32 v[34:35], v[12:13], v[122:123], v[34:35] op_sel:[0,1,0]
	v_pk_fma_f32 v[8:9], v[20:21], v[128:129], v[30:31] op_sel:[0,1,0]
	v_pk_fma_f32 v[10:11], v[20:21], v[130:131], v[32:33] op_sel_hi:[1,0,1]
	v_pk_fma_f32 v[12:13], v[20:21], v[130:131], v[34:35] op_sel:[0,1,0]
	v_pk_mul_f32 v[36:37], v[150:151], v[140:141] op_sel_hi:[1,0]
	v_pk_mul_f32 v[38:39], v[150:151], v[140:141] op_sel:[0,1]
	v_pk_mul_f32 v[42:43], v[2:3], v[142:143] op_sel_hi:[1,0]
	v_pk_fma_f32 v[36:37], v[14:15], v[124:125], v[36:37] op_sel_hi:[1,0,1]
	v_pk_fma_f32 v[38:39], v[16:17], v[124:125], v[38:39] op_sel:[0,1,0]
	v_pk_fma_f32 v[42:43], v[4:5], v[142:143], v[42:43] op_sel:[0,1,0]
	v_pk_fma_f32 v[14:15], v[20:21], v[132:133], v[36:37] op_sel_hi:[1,0,1]
	v_pk_fma_f32 v[16:17], v[20:21], v[132:133], v[38:39] op_sel:[0,1,0]
	v_pk_fma_f32 v[42:43], v[6:7], v[144:145], v[42:43] op_sel_hi:[1,0,1]
	v_pk_fma_f32 v[42:43], v[8:9], v[144:145], v[42:43] op_sel:[0,1,0]
	v_pk_fma_f32 v[42:43], v[10:11], v[146:147], v[42:43] op_sel_hi:[1,0,1]
	v_pk_fma_f32 v[42:43], v[12:13], v[146:147], v[42:43] op_sel:[0,1,0]
	v_pk_fma_f32 v[42:43], v[14:15], v[148:149], v[42:43] op_sel_hi:[1,0,1]
	v_pk_fma_f32 v[42:43], v[16:17], v[148:149], v[42:43] op_sel:[0,1,0]
	s_waitcnt lgkmcnt(0)
; __device__ __forceinline__ void rwkv_block(KP p, int o, int b, int hd, LAS unsigned char* lds, const bf16_t* P, bf16_t* YB) {
;     ...
;             for (int tt = 0; tt < 16; ++tt) {
;                 const int o8 = tt * 64 + c * 8;
;                 const f32x4 ka = *(const LAS f32x4*)(KK + o8), kb = *(const LAS f32x4*)(KK + o8 + 4);
;                 const f32x4 wa = *(const LAS f32x4*)(Wd + o8), wb = *(const LAS f32x4*)(Wd + o8 + 4);
;                 const f32x4 ba = *(const LAS f32x4*)(BB + o8), bb = *(const LAS f32x4*)(BB + o8 + 4);
;                 const f32x4 ma = *(const LAS f32x4*)(KM + o8), mb = *(const LAS f32x4*)(KM + o8 + 4);
;                 const f32x4 ra = *(const LAS f32x4*)(Rr + o8), rb = *(const LAS f32x4*)(Rr + o8 + 4);
;                 const f32x2 v01 = *(const LAS f32x2*)(Vv + tt * 64 + 2 * rp);
;                 const f32x2 k2[4] = {{ka[0], ka[1]}, {ka[2], ka[3]}, {kb[0], kb[1]}, {kb[2], kb[3]}};
;                 const f32x2 w2[4] = {{wa[0], wa[1]}, {wa[2], wa[3]}, {wb[0], wb[1]}, {wb[2], wb[3]}};
;                 const f32x2 b2[4] = {{ba[0], ba[1]}, {ba[2], ba[3]}, {bb[0], bb[1]}, {bb[2], bb[3]}};
;                 const f32x2 m2[4] = {{ma[0], ma[1]}, {ma[2], ma[3]}, {mb[0], mb[1]}, {mb[2], mb[3]}};
;                 const f32x2 r2[4] = {{ra[0], ra[1]}, {ra[2], ra[3]}, {rb[0], rb[1]}, {rb[2], rb[3]}};
;                 f32x2 accA = s[0][0] * k2[0], accB = s[1][0] * k2[0], accA2 = s[0][2] * k2[2], accB2 = s[1][2] * k2[2];
;                 accA = s[0][1] * k2[1] + accA; accB = s[1][1] * k2[1] + accB; accA2 = s[0][3] * k2[3] + accA2; accB2 = s[1][3] * k2[3] + accB2;
;                 accA = accA + accA2; accB = accB + accB2;
;                 float sa0 = accA.x + accA.y, sa1 = accB.x + accB.y;
;                 sa0 += dpp_f<0xB1>(sa0); sa1 += dpp_f<0xB1>(sa1);
;                 sa0 += dpp_f<0x4E>(sa0); sa1 += dpp_f<0x4E>(sa1);
;                 sa0 += dpp_f<0x141>(sa0); sa1 += dpp_f<0x141>(sa1);
;                 const f32x2 saA = {sa0, sa0}, saB = {sa1, sa1}, vA = {v01.x, v01.x}, vB = {v01.y, v01.y};
;                 f32x2 yA, yB;
; #pragma unroll
;                 for (int j = 0; j < 4; ++j) {
;                     f32x2 tA = vA * m2[j], tB = vB * m2[j];
;                     tA = saA * b2[j] + tA; tB = saB * b2[j] + tB;
;                     s[0][j] = s[0][j] * w2[j] + tA; s[1][j] = s[1][j] * w2[j] + tB;
	v_pk_mul_f32 v[20:21], v[2:3], v[64:65] op_sel_hi:[1,0]
	ds_read_b128 v[110:113], v180 offset:6400
	ds_read_b128 v[114:117], v180 offset:6416
	v_pk_fma_f32 v[20:21], v[4:5], v[64:65], v[20:21] op_sel:[0,1,0]
	ds_read_b64 v[150:151], v181 offset:22784
	ds_read_b128 v[134:137], v180 offset:14592
	v_pk_fma_f32 v[20:21], v[6:7], v[66:67], v[20:21] op_sel_hi:[1,0,1]
	ds_read_b128 v[138:141], v180 offset:14608
	ds_read_b128 v[118:121], v180 offset:2304
	v_pk_fma_f32 v[20:21], v[8:9], v[66:67], v[20:21] op_sel:[0,1,0]
	ds_read_b128 v[122:125], v180 offset:2320
	ds_read_b128 v[126:129], v180 offset:10496
	v_pk_fma_f32 v[20:21], v[10:11], v[68:69], v[20:21] op_sel_hi:[1,0,1]
	ds_read_b128 v[130:133], v180 offset:10512
	ds_read_b128 v[142:145], v180 offset:18688
	v_pk_fma_f32 v[20:21], v[12:13], v[68:69], v[20:21] op_sel:[0,1,0]
	ds_read_b128 v[146:149], v180 offset:18704
	v_add_f32_dpp v42, v42, v42 quad_perm:[1,0,3,2] row_mask:0xf bank_mask:0xf bound_ctrl:1
	v_pk_fma_f32 v[20:21], v[14:15], v[70:71], v[20:21] op_sel_hi:[1,0,1]
	v_add_f32_dpp v43, v43, v43 quad_perm:[1,0,3,2] row_mask:0xf bank_mask:0xf bound_ctrl:1
	v_add_f32_dpp v42, v42, v42 quad_perm:[2,3,0,1] row_mask:0xf bank_mask:0xf bound_ctrl:1
	v_pk_fma_f32 v[20:21], v[16:17], v[70:71], v[20:21] op_sel:[0,1,0]
	v_add_f32_dpp v43, v43, v43 quad_perm:[2,3,0,1] row_mask:0xf bank_mask:0xf bound_ctrl:1
	v_add_f32_dpp v42, v42, v42 row_half_mirror row_mask:0xf bank_mask:0xf bound_ctrl:1
	v_add_f32_dpp v20, v20, v20 quad_perm:[1,0,3,2] row_mask:0xf bank_mask:0xf bound_ctrl:1
	v_add_f32_dpp v21, v21, v21 quad_perm:[1,0,3,2] row_mask:0xf bank_mask:0xf bound_ctrl:1
	v_add_f32_dpp v43, v43, v43 row_half_mirror row_mask:0xf bank_mask:0xf bound_ctrl:1
	v_add_f32_dpp v20, v20, v20 quad_perm:[2,3,0,1] row_mask:0xf bank_mask:0xf bound_ctrl:1
	v_add_f32_dpp v21, v21, v21 quad_perm:[2,3,0,1] row_mask:0xf bank_mask:0xf bound_ctrl:1
	ds_write_b64 v184, v[42:43] offset:30464
	v_add_f32_dpp v20, v20, v20 row_half_mirror row_mask:0xf bank_mask:0xf bound_ctrl:1
	v_add_f32_dpp v21, v21, v21 row_half_mirror row_mask:0xf bank_mask:0xf bound_ctrl:1
	v_pk_mul_f32 v[24:25], v[104:105], v[88:89] op_sel_hi:[1,0]
	v_pk_mul_f32 v[26:27], v[104:105], v[88:89] op_sel:[0,1]
	v_pk_mul_f32 v[28:29], v[104:105], v[90:91] op_sel_hi:[1,0]
	v_pk_fma_f32 v[24:25], v[2:3], v[72:73], v[24:25] op_sel_hi:[1,0,1]
	v_pk_fma_f32 v[26:27], v[4:5], v[72:73], v[26:27] op_sel:[0,1,0]
	v_pk_fma_f32 v[28:29], v[6:7], v[74:75], v[28:29] op_sel_hi:[1,0,1]
	v_pk_fma_f32 v[2:3], v[20:21], v[80:81], v[24:25] op_sel_hi:[1,0,1]
	v_pk_fma_f32 v[4:5], v[20:21], v[80:81], v[26:27] op_sel:[0,1,0]
	v_pk_fma_f32 v[6:7], v[20:21], v[82:83], v[28:29] op_sel_hi:[1,0,1]
	v_pk_mul_f32 v[30:31], v[104:105], v[90:91] op_sel:[0,1]
	v_pk_mul_f32 v[32:33], v[104:105], v[92:93] op_sel_hi:[1,0]
	v_pk_mul_f32 v[34:35], v[104:105], v[92:93] op_sel:[0,1]
	v_pk_fma_f32 v[30:31], v[8:9], v[74:75], v[30:31] op_sel:[0,1,0]
	v_pk_fma_f32 v[32:33], v[10:11], v[76:77], v[32:33] op_sel_hi:[1,0,1]
	v_pk_fma_f32 v[34:35], v[12:13], v[76:77], v[34:35] op_sel:[0,1,0]
	v_pk_fma_f32 v[8:9], v[20:21], v[82:83], v[30:31] op_sel:[0,1,0]
	v_pk_fma_f32 v[10:11], v[20:21], v[84:85], v[32:33] op_sel_hi:[1,0,1]
	v_pk_fma_f32 v[12:13], v[20:21], v[84:85], v[34:35] op_sel:[0,1,0]
	v_pk_mul_f32 v[36:37], v[104:105], v[94:95] op_sel_hi:[1,0]
	v_pk_mul_f32 v[38:39], v[104:105], v[94:95] op_sel:[0,1]
	v_pk_mul_f32 v[40:41], v[2:3], v[96:97] op_sel_hi:[1,0]
	v_pk_fma_f32 v[36:37], v[14:15], v[78:79], v[36:37] op_sel_hi:[1,0,1]
	v_pk_fma_f32 v[38:39], v[16:17], v[78:79], v[38:39] op_sel:[0,1,0]
	v_pk_fma_f32 v[40:41], v[4:5], v[96:97], v[40:41] op_sel:[0,1,0]
	v_pk_fma_f32 v[14:15], v[20:21], v[86:87], v[36:37] op_sel_hi:[1,0,1]
	v_pk_fma_f32 v[16:17], v[20:21], v[86:87], v[38:39] op_sel:[0,1,0]
	v_pk_fma_f32 v[40:41], v[6:7], v[98:99], v[40:41] op_sel_hi:[1,0,1]
	v_pk_fma_f32 v[40:41], v[8:9], v[98:99], v[40:41] op_sel:[0,1,0]
	v_pk_fma_f32 v[40:41], v[10:11], v[100:101], v[40:41] op_sel_hi:[1,0,1]
	v_pk_fma_f32 v[40:41], v[12:13], v[100:101], v[40:41] op_sel:[0,1,0]
	v_pk_fma_f32 v[40:41], v[14:15], v[102:103], v[40:41] op_sel_hi:[1,0,1]
	v_pk_fma_f32 v[40:41], v[16:17], v[102:103], v[40:41] op_sel:[0,1,0]
	s_waitcnt lgkmcnt(0)
; __device__ __forceinline__ void rwkv_block(KP p, int o, int b, int hd, LAS unsigned char* lds, const bf16_t* P, bf16_t* YB) {
;     ...
;             for (int tt = 0; tt < 16; ++tt) {
;                 const int o8 = tt * 64 + c * 8;
;                 const f32x4 ka = *(const LAS f32x4*)(KK + o8), kb = *(const LAS f32x4*)(KK + o8 + 4);
;                 const f32x4 wa = *(const LAS f32x4*)(Wd + o8), wb = *(const LAS f32x4*)(Wd + o8 + 4);
;                 const f32x4 ba = *(const LAS f32x4*)(BB + o8), bb = *(const LAS f32x4*)(BB + o8 + 4);
;                 const f32x4 ma = *(const LAS f32x4*)(KM + o8), mb = *(const LAS f32x4*)(KM + o8 + 4);
;                 const f32x4 ra = *(const LAS f32x4*)(Rr + o8), rb = *(const LAS f32x4*)(Rr + o8 + 4);
;                 const f32x2 v01 = *(const LAS f32x2*)(Vv + tt * 64 + 2 * rp);
;                 const f32x2 k2[4] = {{ka[0], ka[1]}, {ka[2], ka[3]}, {kb[0], kb[1]}, {kb[2], kb[3]}};
;                 const f32x2 w2[4] = {{wa[0], wa[1]}, {wa[2], wa[3]}, {wb[0], wb[1]}, {wb[2], wb[3]}};
;                 const f32x2 b2[4] = {{ba[0], ba[1]}, {ba[2], ba[3]}, {bb[0], bb[1]}, {bb[2], bb[3]}};
;                 const f32x2 m2[4] = {{ma[0], ma[1]}, {ma[2], ma[3]}, {mb[0], mb[1]}, {mb[2], mb[3]}};
;                 const f32x2 r2[4] = {{ra[0], ra[1]}, {ra[2], ra[3]}, {rb[0], rb[1]}, {rb[2], rb[3]}};
;                 f32x2 accA = s[0][0] * k2[0], accB = s[1][0] * k2[0], accA2 = s[0][2] * k2[2], accB2 = s[1][2] * k2[2];
;                 accA = s[0][1] * k2[1] + accA; accB = s[1][1] * k2[1] + accB; accA2 = s[0][3] * k2[3] + accA2; accB2 = s[1][3] * k2[3] + accB2;
;                 accA = accA + accA2; accB = accB + accB2;
;                 float sa0 = accA.x + accA.y, sa1 = accB.x + accB.y;
;                 sa0 += dpp_f<0xB1>(sa0); sa1 += dpp_f<0xB1>(sa1);
;                 sa0 += dpp_f<0x4E>(sa0); sa1 += dpp_f<0x4E>(sa1);
;                 sa0 += dpp_f<0x141>(sa0); sa1 += dpp_f<0x141>(sa1);
;                 const f32x2 saA = {sa0, sa0}, saB = {sa1, sa1}, vA = {v01.x, v01.x}, vB = {v01.y, v01.y};
;                 f32x2 yA, yB;
; #pragma unroll
;                 for (int j = 0; j < 4; ++j) {
;                     f32x2 tA = vA * m2[j], tB = vB * m2[j];
;                     tA = saA * b2[j] + tA; tB = saB * b2[j] + tB;
;                     s[0][j] = s[0][j] * w2[j] + tA; s[1][j] = s[1][j] * w2[j] + tB;
	v_pk_mul_f32 v[20:21], v[2:3], v[110:111] op_sel_hi:[1,0]
	ds_read_b128 v[64:67], v180 offset:6656
	ds_read_b128 v[68:71], v180 offset:6672
	v_pk_fma_f32 v[20:21], v[4:5], v[110:111], v[20:21] op_sel:[0,1,0]
	ds_read_b64 v[104:105], v181 offset:23040
	ds_read_b128 v[88:91], v180 offset:14848
	v_pk_fma_f32 v[20:21], v[6:7], v[112:113], v[20:21] op_sel_hi:[1,0,1]
	ds_read_b128 v[92:95], v180 offset:14864
	ds_read_b128 v[72:75], v180 offset:2560
	v_pk_fma_f32 v[20:21], v[8:9], v[112:113], v[20:21] op_sel:[0,1,0]
	ds_read_b128 v[76:79], v180 offset:2576
	ds_read_b128 v[80:83], v180 offset:10752
	v_pk_fma_f32 v[20:21], v[10:11], v[114:115], v[20:21] op_sel_hi:[1,0,1]
	ds_read_b128 v[84:87], v180 offset:10768
	ds_read_b128 v[96:99], v180 offset:18944
	v_pk_fma_f32 v[20:21], v[12:13], v[114:115], v[20:21] op_sel:[0,1,0]
	ds_read_b128 v[100:103], v180 offset:18960
	v_add_f32_dpp v40, v40, v40 quad_perm:[1,0,3,2] row_mask:0xf bank_mask:0xf bound_ctrl:1
	v_pk_fma_f32 v[20:21], v[14:15], v[116:117], v[20:21] op_sel_hi:[1,0,1]
	v_add_f32_dpp v41, v41, v41 quad_perm:[1,0,3,2] row_mask:0xf bank_mask:0xf bound_ctrl:1
	v_add_f32_dpp v40, v40, v40 quad_perm:[2,3,0,1] row_mask:0xf bank_mask:0xf bound_ctrl:1
	v_pk_fma_f32 v[20:21], v[16:17], v[116:117], v[20:21] op_sel:[0,1,0]
	v_add_f32_dpp v41, v41, v41 quad_perm:[2,3,0,1] row_mask:0xf bank_mask:0xf bound_ctrl:1
	v_add_f32_dpp v40, v40, v40 row_half_mirror row_mask:0xf bank_mask:0xf bound_ctrl:1
	v_add_f32_dpp v20, v20, v20 quad_perm:[1,0,3,2] row_mask:0xf bank_mask:0xf bound_ctrl:1
	v_add_f32_dpp v21, v21, v21 quad_perm:[1,0,3,2] row_mask:0xf bank_mask:0xf bound_ctrl:1
	v_add_f32_dpp v41, v41, v41 row_half_mirror row_mask:0xf bank_mask:0xf bound_ctrl:1
	v_add_f32_dpp v20, v20, v20 quad_perm:[2,3,0,1] row_mask:0xf bank_mask:0xf bound_ctrl:1
	v_add_f32_dpp v21, v21, v21 quad_perm:[2,3,0,1] row_mask:0xf bank_mask:0xf bound_ctrl:1
	ds_write_b64 v184, v[40:41] offset:30720
	v_add_f32_dpp v20, v20, v20 row_half_mirror row_mask:0xf bank_mask:0xf bound_ctrl:1
	v_add_f32_dpp v21, v21, v21 row_half_mirror row_mask:0xf bank_mask:0xf bound_ctrl:1
	v_pk_mul_f32 v[24:25], v[150:151], v[134:135] op_sel_hi:[1,0]
	v_pk_mul_f32 v[26:27], v[150:151], v[134:135] op_sel:[0,1]
	v_pk_mul_f32 v[28:29], v[150:151], v[136:137] op_sel_hi:[1,0]
	v_pk_fma_f32 v[24:25], v[2:3], v[118:119], v[24:25] op_sel_hi:[1,0,1]
	v_pk_fma_f32 v[26:27], v[4:5], v[118:119], v[26:27] op_sel:[0,1,0]
	v_pk_fma_f32 v[28:29], v[6:7], v[120:121], v[28:29] op_sel_hi:[1,0,1]
	v_pk_fma_f32 v[2:3], v[20:21], v[126:127], v[24:25] op_sel_hi:[1,0,1]
	v_pk_fma_f32 v[4:5], v[20:21], v[126:127], v[26:27] op_sel:[0,1,0]
	v_pk_fma_f32 v[6:7], v[20:21], v[128:129], v[28:29] op_sel_hi:[1,0,1]
	v_pk_mul_f32 v[30:31], v[150:151], v[136:137] op_sel:[0,1]
	v_pk_mul_f32 v[32:33], v[150:151], v[138:139] op_sel_hi:[1,0]
	v_pk_mul_f32 v[34:35], v[150:151], v[138:139] op_sel:[0,1]
	v_pk_fma_f32 v[30:31], v[8:9], v[120:121], v[30:31] op_sel:[0,1,0]
	v_pk_fma_f32 v[32:33], v[10:11], v[122:123], v[32:33] op_sel_hi:[1,0,1]
	v_pk_fma_f32 v[34:35], v[12:13], v[122:123], v[34:35] op_sel:[0,1,0]
	v_pk_fma_f32 v[8:9], v[20:21], v[128:129], v[30:31] op_sel:[0,1,0]
	v_pk_fma_f32 v[10:11], v[20:21], v[130:131], v[32:33] op_sel_hi:[1,0,1]
	v_pk_fma_f32 v[12:13], v[20:21], v[130:131], v[34:35] op_sel:[0,1,0]
	v_pk_mul_f32 v[36:37], v[150:151], v[140:141] op_sel_hi:[1,0]
	v_pk_mul_f32 v[38:39], v[150:151], v[140:141] op_sel:[0,1]
	v_pk_mul_f32 v[42:43], v[2:3], v[142:143] op_sel_hi:[1,0]
	v_pk_fma_f32 v[36:37], v[14:15], v[124:125], v[36:37] op_sel_hi:[1,0,1]
	v_pk_fma_f32 v[38:39], v[16:17], v[124:125], v[38:39] op_sel:[0,1,0]
	v_pk_fma_f32 v[42:43], v[4:5], v[142:143], v[42:43] op_sel:[0,1,0]
	v_pk_fma_f32 v[14:15], v[20:21], v[132:133], v[36:37] op_sel_hi:[1,0,1]
	v_pk_fma_f32 v[16:17], v[20:21], v[132:133], v[38:39] op_sel:[0,1,0]
	v_pk_fma_f32 v[42:43], v[6:7], v[144:145], v[42:43] op_sel_hi:[1,0,1]
	v_pk_fma_f32 v[42:43], v[8:9], v[144:145], v[42:43] op_sel:[0,1,0]
	v_pk_fma_f32 v[42:43], v[10:11], v[146:147], v[42:43] op_sel_hi:[1,0,1]
	v_pk_fma_f32 v[42:43], v[12:13], v[146:147], v[42:43] op_sel:[0,1,0]
	v_pk_fma_f32 v[42:43], v[14:15], v[148:149], v[42:43] op_sel_hi:[1,0,1]
	v_pk_fma_f32 v[42:43], v[16:17], v[148:149], v[42:43] op_sel:[0,1,0]
	s_waitcnt lgkmcnt(0)
; __device__ __forceinline__ void rwkv_block(KP p, int o, int b, int hd, LAS unsigned char* lds, const bf16_t* P, bf16_t* YB) {
;     ...
;             for (int tt = 0; tt < 16; ++tt) {
;                 const int o8 = tt * 64 + c * 8;
;                 const f32x4 ka = *(const LAS f32x4*)(KK + o8), kb = *(const LAS f32x4*)(KK + o8 + 4);
;                 const f32x4 wa = *(const LAS f32x4*)(Wd + o8), wb = *(const LAS f32x4*)(Wd + o8 + 4);
;                 const f32x4 ba = *(const LAS f32x4*)(BB + o8), bb = *(const LAS f32x4*)(BB + o8 + 4);
;                 const f32x4 ma = *(const LAS f32x4*)(KM + o8), mb = *(const LAS f32x4*)(KM + o8 + 4);
;                 const f32x4 ra = *(const LAS f32x4*)(Rr + o8), rb = *(const LAS f32x4*)(Rr + o8 + 4);
;                 const f32x2 v01 = *(const LAS f32x2*)(Vv + tt * 64 + 2 * rp);
;                 const f32x2 k2[4] = {{ka[0], ka[1]}, {ka[2], ka[3]}, {kb[0], kb[1]}, {kb[2], kb[3]}};
;                 const f32x2 w2[4] = {{wa[0], wa[1]}, {wa[2], wa[3]}, {wb[0], wb[1]}, {wb[2], wb[3]}};
;                 const f32x2 b2[4] = {{ba[0], ba[1]}, {ba[2], ba[3]}, {bb[0], bb[1]}, {bb[2], bb[3]}};
;                 const f32x2 m2[4] = {{ma[0], ma[1]}, {ma[2], ma[3]}, {mb[0], mb[1]}, {mb[2], mb[3]}};
;                 const f32x2 r2[4] = {{ra[0], ra[1]}, {ra[2], ra[3]}, {rb[0], rb[1]}, {rb[2], rb[3]}};
;                 f32x2 accA = s[0][0] * k2[0], accB = s[1][0] * k2[0], accA2 = s[0][2] * k2[2], accB2 = s[1][2] * k2[2];
;                 accA = s[0][1] * k2[1] + accA; accB = s[1][1] * k2[1] + accB; accA2 = s[0][3] * k2[3] + accA2; accB2 = s[1][3] * k2[3] + accB2;
;                 accA = accA + accA2; accB = accB + accB2;
;                 float sa0 = accA.x + accA.y, sa1 = accB.x + accB.y;
;                 sa0 += dpp_f<0xB1>(sa0); sa1 += dpp_f<0xB1>(sa1);
;                 sa0 += dpp_f<0x4E>(sa0); sa1 += dpp_f<0x4E>(sa1);
;                 sa0 += dpp_f<0x141>(sa0); sa1 += dpp_f<0x141>(sa1);
;                 const f32x2 saA = {sa0, sa0}, saB = {sa1, sa1}, vA = {v01.x, v01.x}, vB = {v01.y, v01.y};
;                 f32x2 yA, yB;
; #pragma unroll
;                 for (int j = 0; j < 4; ++j) {
;                     f32x2 tA = vA * m2[j], tB = vB * m2[j];
;                     tA = saA * b2[j] + tA; tB = saB * b2[j] + tB;
;                     s[0][j] = s[0][j] * w2[j] + tA; s[1][j] = s[1][j] * w2[j] + tB;
	v_pk_mul_f32 v[20:21], v[2:3], v[64:65] op_sel_hi:[1,0]
	ds_read_b128 v[110:113], v180 offset:6912
	ds_read_b128 v[114:117], v180 offset:6928
	v_pk_fma_f32 v[20:21], v[4:5], v[64:65], v[20:21] op_sel:[0,1,0]
	ds_read_b64 v[150:151], v181 offset:23296
	ds_read_b128 v[134:137], v180 offset:15104
	v_pk_fma_f32 v[20:21], v[6:7], v[66:67], v[20:21] op_sel_hi:[1,0,1]
	ds_read_b128 v[138:141], v180 offset:15120
	ds_read_b128 v[118:121], v180 offset:2816
	v_pk_fma_f32 v[20:21], v[8:9], v[66:67], v[20:21] op_sel:[0,1,0]
	ds_read_b128 v[122:125], v180 offset:2832
	ds_read_b128 v[126:129], v180 offset:11008
	v_pk_fma_f32 v[20:21], v[10:11], v[68:69], v[20:21] op_sel_hi:[1,0,1]
	ds_read_b128 v[130:133], v180 offset:11024
	ds_read_b128 v[142:145], v180 offset:19200
	v_pk_fma_f32 v[20:21], v[12:13], v[68:69], v[20:21] op_sel:[0,1,0]
	ds_read_b128 v[146:149], v180 offset:19216
	v_add_f32_dpp v42, v42, v42 quad_perm:[1,0,3,2] row_mask:0xf bank_mask:0xf bound_ctrl:1
	v_pk_fma_f32 v[20:21], v[14:15], v[70:71], v[20:21] op_sel_hi:[1,0,1]
	v_add_f32_dpp v43, v43, v43 quad_perm:[1,0,3,2] row_mask:0xf bank_mask:0xf bound_ctrl:1
	v_add_f32_dpp v42, v42, v42 quad_perm:[2,3,0,1] row_mask:0xf bank_mask:0xf bound_ctrl:1
	v_pk_fma_f32 v[20:21], v[16:17], v[70:71], v[20:21] op_sel:[0,1,0]
	v_add_f32_dpp v43, v43, v43 quad_perm:[2,3,0,1] row_mask:0xf bank_mask:0xf bound_ctrl:1
	v_add_f32_dpp v42, v42, v42 row_half_mirror row_mask:0xf bank_mask:0xf bound_ctrl:1
	v_add_f32_dpp v20, v20, v20 quad_perm:[1,0,3,2] row_mask:0xf bank_mask:0xf bound_ctrl:1
	v_add_f32_dpp v21, v21, v21 quad_perm:[1,0,3,2] row_mask:0xf bank_mask:0xf bound_ctrl:1
	v_add_f32_dpp v43, v43, v43 row_half_mirror row_mask:0xf bank_mask:0xf bound_ctrl:1
	v_add_f32_dpp v20, v20, v20 quad_perm:[2,3,0,1] row_mask:0xf bank_mask:0xf bound_ctrl:1
	v_add_f32_dpp v21, v21, v21 quad_perm:[2,3,0,1] row_mask:0xf bank_mask:0xf bound_ctrl:1
	ds_write_b64 v184, v[42:43] offset:30976
	v_add_f32_dpp v20, v20, v20 row_half_mirror row_mask:0xf bank_mask:0xf bound_ctrl:1
	v_add_f32_dpp v21, v21, v21 row_half_mirror row_mask:0xf bank_mask:0xf bound_ctrl:1
	v_pk_mul_f32 v[24:25], v[104:105], v[88:89] op_sel_hi:[1,0]
	v_pk_mul_f32 v[26:27], v[104:105], v[88:89] op_sel:[0,1]
	v_pk_mul_f32 v[28:29], v[104:105], v[90:91] op_sel_hi:[1,0]
	v_pk_fma_f32 v[24:25], v[2:3], v[72:73], v[24:25] op_sel_hi:[1,0,1]
	v_pk_fma_f32 v[26:27], v[4:5], v[72:73], v[26:27] op_sel:[0,1,0]
	v_pk_fma_f32 v[28:29], v[6:7], v[74:75], v[28:29] op_sel_hi:[1,0,1]
	v_pk_fma_f32 v[2:3], v[20:21], v[80:81], v[24:25] op_sel_hi:[1,0,1]
	v_pk_fma_f32 v[4:5], v[20:21], v[80:81], v[26:27] op_sel:[0,1,0]
	v_pk_fma_f32 v[6:7], v[20:21], v[82:83], v[28:29] op_sel_hi:[1,0,1]
	v_pk_mul_f32 v[30:31], v[104:105], v[90:91] op_sel:[0,1]
	v_pk_mul_f32 v[32:33], v[104:105], v[92:93] op_sel_hi:[1,0]
	v_pk_mul_f32 v[34:35], v[104:105], v[92:93] op_sel:[0,1]
	v_pk_fma_f32 v[30:31], v[8:9], v[74:75], v[30:31] op_sel:[0,1,0]
	v_pk_fma_f32 v[32:33], v[10:11], v[76:77], v[32:33] op_sel_hi:[1,0,1]
	v_pk_fma_f32 v[34:35], v[12:13], v[76:77], v[34:35] op_sel:[0,1,0]
	v_pk_fma_f32 v[8:9], v[20:21], v[82:83], v[30:31] op_sel:[0,1,0]
	v_pk_fma_f32 v[10:11], v[20:21], v[84:85], v[32:33] op_sel_hi:[1,0,1]
	v_pk_fma_f32 v[12:13], v[20:21], v[84:85], v[34:35] op_sel:[0,1,0]
	v_pk_mul_f32 v[36:37], v[104:105], v[94:95] op_sel_hi:[1,0]
	v_pk_mul_f32 v[38:39], v[104:105], v[94:95] op_sel:[0,1]
	v_pk_mul_f32 v[40:41], v[2:3], v[96:97] op_sel_hi:[1,0]
	v_pk_fma_f32 v[36:37], v[14:15], v[78:79], v[36:37] op_sel_hi:[1,0,1]
	v_pk_fma_f32 v[38:39], v[16:17], v[78:79], v[38:39] op_sel:[0,1,0]
	v_pk_fma_f32 v[40:41], v[4:5], v[96:97], v[40:41] op_sel:[0,1,0]
	v_pk_fma_f32 v[14:15], v[20:21], v[86:87], v[36:37] op_sel_hi:[1,0,1]
	v_pk_fma_f32 v[16:17], v[20:21], v[86:87], v[38:39] op_sel:[0,1,0]
	v_pk_fma_f32 v[40:41], v[6:7], v[98:99], v[40:41] op_sel_hi:[1,0,1]
	v_pk_fma_f32 v[40:41], v[8:9], v[98:99], v[40:41] op_sel:[0,1,0]
	v_pk_fma_f32 v[40:41], v[10:11], v[100:101], v[40:41] op_sel_hi:[1,0,1]
	v_pk_fma_f32 v[40:41], v[12:13], v[100:101], v[40:41] op_sel:[0,1,0]
	v_pk_fma_f32 v[40:41], v[14:15], v[102:103], v[40:41] op_sel_hi:[1,0,1]
	v_pk_fma_f32 v[40:41], v[16:17], v[102:103], v[40:41] op_sel:[0,1,0]
	s_waitcnt lgkmcnt(0)
; __device__ __forceinline__ void rwkv_block(KP p, int o, int b, int hd, LAS unsigned char* lds, const bf16_t* P, bf16_t* YB) {
;     ...
;             for (int tt = 0; tt < 16; ++tt) {
;                 const int o8 = tt * 64 + c * 8;
;                 const f32x4 ka = *(const LAS f32x4*)(KK + o8), kb = *(const LAS f32x4*)(KK + o8 + 4);
;                 const f32x4 wa = *(const LAS f32x4*)(Wd + o8), wb = *(const LAS f32x4*)(Wd + o8 + 4);
;                 const f32x4 ba = *(const LAS f32x4*)(BB + o8), bb = *(const LAS f32x4*)(BB + o8 + 4);
;                 const f32x4 ma = *(const LAS f32x4*)(KM + o8), mb = *(const LAS f32x4*)(KM + o8 + 4);
;                 const f32x4 ra = *(const LAS f32x4*)(Rr + o8), rb = *(const LAS f32x4*)(Rr + o8 + 4);
;                 const f32x2 v01 = *(const LAS f32x2*)(Vv + tt * 64 + 2 * rp);
;                 const f32x2 k2[4] = {{ka[0], ka[1]}, {ka[2], ka[3]}, {kb[0], kb[1]}, {kb[2], kb[3]}};
;                 const f32x2 w2[4] = {{wa[0], wa[1]}, {wa[2], wa[3]}, {wb[0], wb[1]}, {wb[2], wb[3]}};
;                 const f32x2 b2[4] = {{ba[0], ba[1]}, {ba[2], ba[3]}, {bb[0], bb[1]}, {bb[2], bb[3]}};
;                 const f32x2 m2[4] = {{ma[0], ma[1]}, {ma[2], ma[3]}, {mb[0], mb[1]}, {mb[2], mb[3]}};
;                 const f32x2 r2[4] = {{ra[0], ra[1]}, {ra[2], ra[3]}, {rb[0], rb[1]}, {rb[2], rb[3]}};
;                 f32x2 accA = s[0][0] * k2[0], accB = s[1][0] * k2[0], accA2 = s[0][2] * k2[2], accB2 = s[1][2] * k2[2];
;                 accA = s[0][1] * k2[1] + accA; accB = s[1][1] * k2[1] + accB; accA2 = s[0][3] * k2[3] + accA2; accB2 = s[1][3] * k2[3] + accB2;
;                 accA = accA + accA2; accB = accB + accB2;
;                 float sa0 = accA.x + accA.y, sa1 = accB.x + accB.y;
;                 sa0 += dpp_f<0xB1>(sa0); sa1 += dpp_f<0xB1>(sa1);
;                 sa0 += dpp_f<0x4E>(sa0); sa1 += dpp_f<0x4E>(sa1);
;                 sa0 += dpp_f<0x141>(sa0); sa1 += dpp_f<0x141>(sa1);
;                 const f32x2 saA = {sa0, sa0}, saB = {sa1, sa1}, vA = {v01.x, v01.x}, vB = {v01.y, v01.y};
;                 f32x2 yA, yB;
; #pragma unroll
;                 for (int j = 0; j < 4; ++j) {
;                     f32x2 tA = vA * m2[j], tB = vB * m2[j];
;                     tA = saA * b2[j] + tA; tB = saB * b2[j] + tB;
;                     s[0][j] = s[0][j] * w2[j] + tA; s[1][j] = s[1][j] * w2[j] + tB;
	v_pk_mul_f32 v[20:21], v[2:3], v[110:111] op_sel_hi:[1,0]
	ds_read_b128 v[64:67], v180 offset:7168
	ds_read_b128 v[68:71], v180 offset:7184
	v_pk_fma_f32 v[20:21], v[4:5], v[110:111], v[20:21] op_sel:[0,1,0]
	ds_read_b64 v[104:105], v181 offset:23552
	ds_read_b128 v[88:91], v180 offset:15360
	v_pk_fma_f32 v[20:21], v[6:7], v[112:113], v[20:21] op_sel_hi:[1,0,1]
	ds_read_b128 v[92:95], v180 offset:15376
	ds_read_b128 v[72:75], v180 offset:3072
	v_pk_fma_f32 v[20:21], v[8:9], v[112:113], v[20:21] op_sel:[0,1,0]
	ds_read_b128 v[76:79], v180 offset:3088
	ds_read_b128 v[80:83], v180 offset:11264
	v_pk_fma_f32 v[20:21], v[10:11], v[114:115], v[20:21] op_sel_hi:[1,0,1]
	ds_read_b128 v[84:87], v180 offset:11280
	ds_read_b128 v[96:99], v180 offset:19456
	v_pk_fma_f32 v[20:21], v[12:13], v[114:115], v[20:21] op_sel:[0,1,0]
	ds_read_b128 v[100:103], v180 offset:19472
	v_add_f32_dpp v40, v40, v40 quad_perm:[1,0,3,2] row_mask:0xf bank_mask:0xf bound_ctrl:1
	v_pk_fma_f32 v[20:21], v[14:15], v[116:117], v[20:21] op_sel_hi:[1,0,1]
	v_add_f32_dpp v41, v41, v41 quad_perm:[1,0,3,2] row_mask:0xf bank_mask:0xf bound_ctrl:1
	v_add_f32_dpp v40, v40, v40 quad_perm:[2,3,0,1] row_mask:0xf bank_mask:0xf bound_ctrl:1
	v_pk_fma_f32 v[20:21], v[16:17], v[116:117], v[20:21] op_sel:[0,1,0]
	v_add_f32_dpp v41, v41, v41 quad_perm:[2,3,0,1] row_mask:0xf bank_mask:0xf bound_ctrl:1
	v_add_f32_dpp v40, v40, v40 row_half_mirror row_mask:0xf bank_mask:0xf bound_ctrl:1
	v_add_f32_dpp v20, v20, v20 quad_perm:[1,0,3,2] row_mask:0xf bank_mask:0xf bound_ctrl:1
	v_add_f32_dpp v21, v21, v21 quad_perm:[1,0,3,2] row_mask:0xf bank_mask:0xf bound_ctrl:1
	v_add_f32_dpp v41, v41, v41 row_half_mirror row_mask:0xf bank_mask:0xf bound_ctrl:1
	v_add_f32_dpp v20, v20, v20 quad_perm:[2,3,0,1] row_mask:0xf bank_mask:0xf bound_ctrl:1
	v_add_f32_dpp v21, v21, v21 quad_perm:[2,3,0,1] row_mask:0xf bank_mask:0xf bound_ctrl:1
	ds_write_b64 v184, v[40:41] offset:31232
	v_add_f32_dpp v20, v20, v20 row_half_mirror row_mask:0xf bank_mask:0xf bound_ctrl:1
	v_add_f32_dpp v21, v21, v21 row_half_mirror row_mask:0xf bank_mask:0xf bound_ctrl:1
	v_pk_mul_f32 v[24:25], v[150:151], v[134:135] op_sel_hi:[1,0]
	v_pk_mul_f32 v[26:27], v[150:151], v[134:135] op_sel:[0,1]
	v_pk_mul_f32 v[28:29], v[150:151], v[136:137] op_sel_hi:[1,0]
	v_pk_fma_f32 v[24:25], v[2:3], v[118:119], v[24:25] op_sel_hi:[1,0,1]
	v_pk_fma_f32 v[26:27], v[4:5], v[118:119], v[26:27] op_sel:[0,1,0]
	v_pk_fma_f32 v[28:29], v[6:7], v[120:121], v[28:29] op_sel_hi:[1,0,1]
	v_pk_fma_f32 v[2:3], v[20:21], v[126:127], v[24:25] op_sel_hi:[1,0,1]
	v_pk_fma_f32 v[4:5], v[20:21], v[126:127], v[26:27] op_sel:[0,1,0]
	v_pk_fma_f32 v[6:7], v[20:21], v[128:129], v[28:29] op_sel_hi:[1,0,1]
	v_pk_mul_f32 v[30:31], v[150:151], v[136:137] op_sel:[0,1]
	v_pk_mul_f32 v[32:33], v[150:151], v[138:139] op_sel_hi:[1,0]
	v_pk_mul_f32 v[34:35], v[150:151], v[138:139] op_sel:[0,1]
	v_pk_fma_f32 v[30:31], v[8:9], v[120:121], v[30:31] op_sel:[0,1,0]
	v_pk_fma_f32 v[32:33], v[10:11], v[122:123], v[32:33] op_sel_hi:[1,0,1]
	v_pk_fma_f32 v[34:35], v[12:13], v[122:123], v[34:35] op_sel:[0,1,0]
	v_pk_fma_f32 v[8:9], v[20:21], v[128:129], v[30:31] op_sel:[0,1,0]
	v_pk_fma_f32 v[10:11], v[20:21], v[130:131], v[32:33] op_sel_hi:[1,0,1]
	v_pk_fma_f32 v[12:13], v[20:21], v[130:131], v[34:35] op_sel:[0,1,0]
	v_pk_mul_f32 v[36:37], v[150:151], v[140:141] op_sel_hi:[1,0]
	v_pk_mul_f32 v[38:39], v[150:151], v[140:141] op_sel:[0,1]
	v_pk_mul_f32 v[42:43], v[2:3], v[142:143] op_sel_hi:[1,0]
	v_pk_fma_f32 v[36:37], v[14:15], v[124:125], v[36:37] op_sel_hi:[1,0,1]
	v_pk_fma_f32 v[38:39], v[16:17], v[124:125], v[38:39] op_sel:[0,1,0]
	v_pk_fma_f32 v[42:43], v[4:5], v[142:143], v[42:43] op_sel:[0,1,0]
	v_pk_fma_f32 v[14:15], v[20:21], v[132:133], v[36:37] op_sel_hi:[1,0,1]
	v_pk_fma_f32 v[16:17], v[20:21], v[132:133], v[38:39] op_sel:[0,1,0]
	v_pk_fma_f32 v[42:43], v[6:7], v[144:145], v[42:43] op_sel_hi:[1,0,1]
	v_pk_fma_f32 v[42:43], v[8:9], v[144:145], v[42:43] op_sel:[0,1,0]
	v_pk_fma_f32 v[42:43], v[10:11], v[146:147], v[42:43] op_sel_hi:[1,0,1]
	v_pk_fma_f32 v[42:43], v[12:13], v[146:147], v[42:43] op_sel:[0,1,0]
	v_pk_fma_f32 v[42:43], v[14:15], v[148:149], v[42:43] op_sel_hi:[1,0,1]
	v_pk_fma_f32 v[42:43], v[16:17], v[148:149], v[42:43] op_sel:[0,1,0]
	s_waitcnt lgkmcnt(0)
; __device__ __forceinline__ void rwkv_block(KP p, int o, int b, int hd, LAS unsigned char* lds, const bf16_t* P, bf16_t* YB) {
;     ...
;             for (int tt = 0; tt < 16; ++tt) {
;                 const int o8 = tt * 64 + c * 8;
;                 const f32x4 ka = *(const LAS f32x4*)(KK + o8), kb = *(const LAS f32x4*)(KK + o8 + 4);
;                 const f32x4 wa = *(const LAS f32x4*)(Wd + o8), wb = *(const LAS f32x4*)(Wd + o8 + 4);
;                 const f32x4 ba = *(const LAS f32x4*)(BB + o8), bb = *(const LAS f32x4*)(BB + o8 + 4);
;                 const f32x4 ma = *(const LAS f32x4*)(KM + o8), mb = *(const LAS f32x4*)(KM + o8 + 4);
;                 const f32x4 ra = *(const LAS f32x4*)(Rr + o8), rb = *(const LAS f32x4*)(Rr + o8 + 4);
;                 const f32x2 v01 = *(const LAS f32x2*)(Vv + tt * 64 + 2 * rp);
;                 const f32x2 k2[4] = {{ka[0], ka[1]}, {ka[2], ka[3]}, {kb[0], kb[1]}, {kb[2], kb[3]}};
;                 const f32x2 w2[4] = {{wa[0], wa[1]}, {wa[2], wa[3]}, {wb[0], wb[1]}, {wb[2], wb[3]}};
;                 const f32x2 b2[4] = {{ba[0], ba[1]}, {ba[2], ba[3]}, {bb[0], bb[1]}, {bb[2], bb[3]}};
;                 const f32x2 m2[4] = {{ma[0], ma[1]}, {ma[2], ma[3]}, {mb[0], mb[1]}, {mb[2], mb[3]}};
;                 const f32x2 r2[4] = {{ra[0], ra[1]}, {ra[2], ra[3]}, {rb[0], rb[1]}, {rb[2], rb[3]}};
;                 f32x2 accA = s[0][0] * k2[0], accB = s[1][0] * k2[0], accA2 = s[0][2] * k2[2], accB2 = s[1][2] * k2[2];
;                 accA = s[0][1] * k2[1] + accA; accB = s[1][1] * k2[1] + accB; accA2 = s[0][3] * k2[3] + accA2; accB2 = s[1][3] * k2[3] + accB2;
;                 accA = accA + accA2; accB = accB + accB2;
;                 float sa0 = accA.x + accA.y, sa1 = accB.x + accB.y;
;                 sa0 += dpp_f<0xB1>(sa0); sa1 += dpp_f<0xB1>(sa1);
;                 sa0 += dpp_f<0x4E>(sa0); sa1 += dpp_f<0x4E>(sa1);
;                 sa0 += dpp_f<0x141>(sa0); sa1 += dpp_f<0x141>(sa1);
;                 const f32x2 saA = {sa0, sa0}, saB = {sa1, sa1}, vA = {v01.x, v01.x}, vB = {v01.y, v01.y};
;                 f32x2 yA, yB;
; #pragma unroll
;                 for (int j = 0; j < 4; ++j) {
;                     f32x2 tA = vA * m2[j], tB = vB * m2[j];
;                     tA = saA * b2[j] + tA; tB = saB * b2[j] + tB;
;                     s[0][j] = s[0][j] * w2[j] + tA; s[1][j] = s[1][j] * w2[j] + tB;
	v_pk_mul_f32 v[20:21], v[2:3], v[64:65] op_sel_hi:[1,0]
	ds_read_b128 v[110:113], v180 offset:7424
	ds_read_b128 v[114:117], v180 offset:7440
	v_pk_fma_f32 v[20:21], v[4:5], v[64:65], v[20:21] op_sel:[0,1,0]
	ds_read_b64 v[150:151], v181 offset:23808
	ds_read_b128 v[134:137], v180 offset:15616
	v_pk_fma_f32 v[20:21], v[6:7], v[66:67], v[20:21] op_sel_hi:[1,0,1]
	ds_read_b128 v[138:141], v180 offset:15632
	ds_read_b128 v[118:121], v180 offset:3328
	v_pk_fma_f32 v[20:21], v[8:9], v[66:67], v[20:21] op_sel:[0,1,0]
	ds_read_b128 v[122:125], v180 offset:3344
	ds_read_b128 v[126:129], v180 offset:11520
	v_pk_fma_f32 v[20:21], v[10:11], v[68:69], v[20:21] op_sel_hi:[1,0,1]
	ds_read_b128 v[130:133], v180 offset:11536
	ds_read_b128 v[142:145], v180 offset:19712
	v_pk_fma_f32 v[20:21], v[12:13], v[68:69], v[20:21] op_sel:[0,1,0]
	ds_read_b128 v[146:149], v180 offset:19728
	v_add_f32_dpp v42, v42, v42 quad_perm:[1,0,3,2] row_mask:0xf bank_mask:0xf bound_ctrl:1
	v_pk_fma_f32 v[20:21], v[14:15], v[70:71], v[20:21] op_sel_hi:[1,0,1]
	v_add_f32_dpp v43, v43, v43 quad_perm:[1,0,3,2] row_mask:0xf bank_mask:0xf bound_ctrl:1
	v_add_f32_dpp v42, v42, v42 quad_perm:[2,3,0,1] row_mask:0xf bank_mask:0xf bound_ctrl:1
	v_pk_fma_f32 v[20:21], v[16:17], v[70:71], v[20:21] op_sel:[0,1,0]
	v_add_f32_dpp v43, v43, v43 quad_perm:[2,3,0,1] row_mask:0xf bank_mask:0xf bound_ctrl:1
	v_add_f32_dpp v42, v42, v42 row_half_mirror row_mask:0xf bank_mask:0xf bound_ctrl:1
	v_add_f32_dpp v20, v20, v20 quad_perm:[1,0,3,2] row_mask:0xf bank_mask:0xf bound_ctrl:1
	v_add_f32_dpp v21, v21, v21 quad_perm:[1,0,3,2] row_mask:0xf bank_mask:0xf bound_ctrl:1
	v_add_f32_dpp v43, v43, v43 row_half_mirror row_mask:0xf bank_mask:0xf bound_ctrl:1
	v_add_f32_dpp v20, v20, v20 quad_perm:[2,3,0,1] row_mask:0xf bank_mask:0xf bound_ctrl:1
	v_add_f32_dpp v21, v21, v21 quad_perm:[2,3,0,1] row_mask:0xf bank_mask:0xf bound_ctrl:1
	ds_write_b64 v184, v[42:43] offset:31488
	v_add_f32_dpp v20, v20, v20 row_half_mirror row_mask:0xf bank_mask:0xf bound_ctrl:1
	v_add_f32_dpp v21, v21, v21 row_half_mirror row_mask:0xf bank_mask:0xf bound_ctrl:1
	v_pk_mul_f32 v[24:25], v[104:105], v[88:89] op_sel_hi:[1,0]
	v_pk_mul_f32 v[26:27], v[104:105], v[88:89] op_sel:[0,1]
	v_pk_mul_f32 v[28:29], v[104:105], v[90:91] op_sel_hi:[1,0]
	v_pk_fma_f32 v[24:25], v[2:3], v[72:73], v[24:25] op_sel_hi:[1,0,1]
	v_pk_fma_f32 v[26:27], v[4:5], v[72:73], v[26:27] op_sel:[0,1,0]
	v_pk_fma_f32 v[28:29], v[6:7], v[74:75], v[28:29] op_sel_hi:[1,0,1]
	v_pk_fma_f32 v[2:3], v[20:21], v[80:81], v[24:25] op_sel_hi:[1,0,1]
	v_pk_fma_f32 v[4:5], v[20:21], v[80:81], v[26:27] op_sel:[0,1,0]
	v_pk_fma_f32 v[6:7], v[20:21], v[82:83], v[28:29] op_sel_hi:[1,0,1]
	v_pk_mul_f32 v[30:31], v[104:105], v[90:91] op_sel:[0,1]
	v_pk_mul_f32 v[32:33], v[104:105], v[92:93] op_sel_hi:[1,0]
	v_pk_mul_f32 v[34:35], v[104:105], v[92:93] op_sel:[0,1]
	v_pk_fma_f32 v[30:31], v[8:9], v[74:75], v[30:31] op_sel:[0,1,0]
	v_pk_fma_f32 v[32:33], v[10:11], v[76:77], v[32:33] op_sel_hi:[1,0,1]
	v_pk_fma_f32 v[34:35], v[12:13], v[76:77], v[34:35] op_sel:[0,1,0]
	v_pk_fma_f32 v[8:9], v[20:21], v[82:83], v[30:31] op_sel:[0,1,0]
	v_pk_fma_f32 v[10:11], v[20:21], v[84:85], v[32:33] op_sel_hi:[1,0,1]
	v_pk_fma_f32 v[12:13], v[20:21], v[84:85], v[34:35] op_sel:[0,1,0]
	v_pk_mul_f32 v[36:37], v[104:105], v[94:95] op_sel_hi:[1,0]
	v_pk_mul_f32 v[38:39], v[104:105], v[94:95] op_sel:[0,1]
	v_pk_mul_f32 v[40:41], v[2:3], v[96:97] op_sel_hi:[1,0]
	v_pk_fma_f32 v[36:37], v[14:15], v[78:79], v[36:37] op_sel_hi:[1,0,1]
	v_pk_fma_f32 v[38:39], v[16:17], v[78:79], v[38:39] op_sel:[0,1,0]
	v_pk_fma_f32 v[40:41], v[4:5], v[96:97], v[40:41] op_sel:[0,1,0]
	v_pk_fma_f32 v[14:15], v[20:21], v[86:87], v[36:37] op_sel_hi:[1,0,1]
	v_pk_fma_f32 v[16:17], v[20:21], v[86:87], v[38:39] op_sel:[0,1,0]
	v_pk_fma_f32 v[40:41], v[6:7], v[98:99], v[40:41] op_sel_hi:[1,0,1]
	v_pk_fma_f32 v[40:41], v[8:9], v[98:99], v[40:41] op_sel:[0,1,0]
	v_pk_fma_f32 v[40:41], v[10:11], v[100:101], v[40:41] op_sel_hi:[1,0,1]
	v_pk_fma_f32 v[40:41], v[12:13], v[100:101], v[40:41] op_sel:[0,1,0]
	v_pk_fma_f32 v[40:41], v[14:15], v[102:103], v[40:41] op_sel_hi:[1,0,1]
	v_pk_fma_f32 v[40:41], v[16:17], v[102:103], v[40:41] op_sel:[0,1,0]
	s_waitcnt lgkmcnt(0)
; __device__ __forceinline__ void rwkv_block(KP p, int o, int b, int hd, LAS unsigned char* lds, const bf16_t* P, bf16_t* YB) {
;     ...
;             for (int tt = 0; tt < 16; ++tt) {
;                 const int o8 = tt * 64 + c * 8;
;                 const f32x4 ka = *(const LAS f32x4*)(KK + o8), kb = *(const LAS f32x4*)(KK + o8 + 4);
;                 const f32x4 wa = *(const LAS f32x4*)(Wd + o8), wb = *(const LAS f32x4*)(Wd + o8 + 4);
;                 const f32x4 ba = *(const LAS f32x4*)(BB + o8), bb = *(const LAS f32x4*)(BB + o8 + 4);
;                 const f32x4 ma = *(const LAS f32x4*)(KM + o8), mb = *(const LAS f32x4*)(KM + o8 + 4);
;                 const f32x4 ra = *(const LAS f32x4*)(Rr + o8), rb = *(const LAS f32x4*)(Rr + o8 + 4);
;                 const f32x2 v01 = *(const LAS f32x2*)(Vv + tt * 64 + 2 * rp);
;                 const f32x2 k2[4] = {{ka[0], ka[1]}, {ka[2], ka[3]}, {kb[0], kb[1]}, {kb[2], kb[3]}};
;                 const f32x2 w2[4] = {{wa[0], wa[1]}, {wa[2], wa[3]}, {wb[0], wb[1]}, {wb[2], wb[3]}};
;                 const f32x2 b2[4] = {{ba[0], ba[1]}, {ba[2], ba[3]}, {bb[0], bb[1]}, {bb[2], bb[3]}};
;                 const f32x2 m2[4] = {{ma[0], ma[1]}, {ma[2], ma[3]}, {mb[0], mb[1]}, {mb[2], mb[3]}};
;                 const f32x2 r2[4] = {{ra[0], ra[1]}, {ra[2], ra[3]}, {rb[0], rb[1]}, {rb[2], rb[3]}};
;                 f32x2 accA = s[0][0] * k2[0], accB = s[1][0] * k2[0], accA2 = s[0][2] * k2[2], accB2 = s[1][2] * k2[2];
;                 accA = s[0][1] * k2[1] + accA; accB = s[1][1] * k2[1] + accB; accA2 = s[0][3] * k2[3] + accA2; accB2 = s[1][3] * k2[3] + accB2;
;                 accA = accA + accA2; accB = accB + accB2;
;                 float sa0 = accA.x + accA.y, sa1 = accB.x + accB.y;
;                 sa0 += dpp_f<0xB1>(sa0); sa1 += dpp_f<0xB1>(sa1);
;                 sa0 += dpp_f<0x4E>(sa0); sa1 += dpp_f<0x4E>(sa1);
;                 sa0 += dpp_f<0x141>(sa0); sa1 += dpp_f<0x141>(sa1);
;                 const f32x2 saA = {sa0, sa0}, saB = {sa1, sa1}, vA = {v01.x, v01.x}, vB = {v01.y, v01.y};
;                 f32x2 yA, yB;
; #pragma unroll
;                 for (int j = 0; j < 4; ++j) {
;                     f32x2 tA = vA * m2[j], tB = vB * m2[j];
;                     tA = saA * b2[j] + tA; tB = saB * b2[j] + tB;
;                     s[0][j] = s[0][j] * w2[j] + tA; s[1][j] = s[1][j] * w2[j] + tB;
	v_pk_mul_f32 v[20:21], v[2:3], v[110:111] op_sel_hi:[1,0]
	ds_read_b128 v[64:67], v180 offset:7680
	ds_read_b128 v[68:71], v180 offset:7696
	v_pk_fma_f32 v[20:21], v[4:5], v[110:111], v[20:21] op_sel:[0,1,0]
	ds_read_b64 v[104:105], v181 offset:24064
	ds_read_b128 v[88:91], v180 offset:15872
	v_pk_fma_f32 v[20:21], v[6:7], v[112:113], v[20:21] op_sel_hi:[1,0,1]
	ds_read_b128 v[92:95], v180 offset:15888
	ds_read_b128 v[72:75], v180 offset:3584
	v_pk_fma_f32 v[20:21], v[8:9], v[112:113], v[20:21] op_sel:[0,1,0]
	ds_read_b128 v[76:79], v180 offset:3600
	ds_read_b128 v[80:83], v180 offset:11776
	v_pk_fma_f32 v[20:21], v[10:11], v[114:115], v[20:21] op_sel_hi:[1,0,1]
	ds_read_b128 v[84:87], v180 offset:11792
	ds_read_b128 v[96:99], v180 offset:19968
	v_pk_fma_f32 v[20:21], v[12:13], v[114:115], v[20:21] op_sel:[0,1,0]
	ds_read_b128 v[100:103], v180 offset:19984
	v_add_f32_dpp v40, v40, v40 quad_perm:[1,0,3,2] row_mask:0xf bank_mask:0xf bound_ctrl:1
	v_pk_fma_f32 v[20:21], v[14:15], v[116:117], v[20:21] op_sel_hi:[1,0,1]
	v_add_f32_dpp v41, v41, v41 quad_perm:[1,0,3,2] row_mask:0xf bank_mask:0xf bound_ctrl:1
	v_add_f32_dpp v40, v40, v40 quad_perm:[2,3,0,1] row_mask:0xf bank_mask:0xf bound_ctrl:1
	v_pk_fma_f32 v[20:21], v[16:17], v[116:117], v[20:21] op_sel:[0,1,0]
	v_add_f32_dpp v41, v41, v41 quad_perm:[2,3,0,1] row_mask:0xf bank_mask:0xf bound_ctrl:1
	v_add_f32_dpp v40, v40, v40 row_half_mirror row_mask:0xf bank_mask:0xf bound_ctrl:1
	v_add_f32_dpp v20, v20, v20 quad_perm:[1,0,3,2] row_mask:0xf bank_mask:0xf bound_ctrl:1
	v_add_f32_dpp v21, v21, v21 quad_perm:[1,0,3,2] row_mask:0xf bank_mask:0xf bound_ctrl:1
	v_add_f32_dpp v41, v41, v41 row_half_mirror row_mask:0xf bank_mask:0xf bound_ctrl:1
	v_add_f32_dpp v20, v20, v20 quad_perm:[2,3,0,1] row_mask:0xf bank_mask:0xf bound_ctrl:1
	v_add_f32_dpp v21, v21, v21 quad_perm:[2,3,0,1] row_mask:0xf bank_mask:0xf bound_ctrl:1
	ds_write_b64 v184, v[40:41] offset:31744
	v_add_f32_dpp v20, v20, v20 row_half_mirror row_mask:0xf bank_mask:0xf bound_ctrl:1
	v_add_f32_dpp v21, v21, v21 row_half_mirror row_mask:0xf bank_mask:0xf bound_ctrl:1
	v_pk_mul_f32 v[24:25], v[150:151], v[134:135] op_sel_hi:[1,0]
	v_pk_mul_f32 v[26:27], v[150:151], v[134:135] op_sel:[0,1]
	v_pk_mul_f32 v[28:29], v[150:151], v[136:137] op_sel_hi:[1,0]
	v_pk_fma_f32 v[24:25], v[2:3], v[118:119], v[24:25] op_sel_hi:[1,0,1]
	v_pk_fma_f32 v[26:27], v[4:5], v[118:119], v[26:27] op_sel:[0,1,0]
	v_pk_fma_f32 v[28:29], v[6:7], v[120:121], v[28:29] op_sel_hi:[1,0,1]
	v_pk_fma_f32 v[2:3], v[20:21], v[126:127], v[24:25] op_sel_hi:[1,0,1]
	v_pk_fma_f32 v[4:5], v[20:21], v[126:127], v[26:27] op_sel:[0,1,0]
	v_pk_fma_f32 v[6:7], v[20:21], v[128:129], v[28:29] op_sel_hi:[1,0,1]
	v_pk_mul_f32 v[30:31], v[150:151], v[136:137] op_sel:[0,1]
	v_pk_mul_f32 v[32:33], v[150:151], v[138:139] op_sel_hi:[1,0]
	v_pk_mul_f32 v[34:35], v[150:151], v[138:139] op_sel:[0,1]
	v_pk_fma_f32 v[30:31], v[8:9], v[120:121], v[30:31] op_sel:[0,1,0]
	v_pk_fma_f32 v[32:33], v[10:11], v[122:123], v[32:33] op_sel_hi:[1,0,1]
	v_pk_fma_f32 v[34:35], v[12:13], v[122:123], v[34:35] op_sel:[0,1,0]
	v_pk_fma_f32 v[8:9], v[20:21], v[128:129], v[30:31] op_sel:[0,1,0]
	v_pk_fma_f32 v[10:11], v[20:21], v[130:131], v[32:33] op_sel_hi:[1,0,1]
	v_pk_fma_f32 v[12:13], v[20:21], v[130:131], v[34:35] op_sel:[0,1,0]
	v_pk_mul_f32 v[36:37], v[150:151], v[140:141] op_sel_hi:[1,0]
	v_pk_mul_f32 v[38:39], v[150:151], v[140:141] op_sel:[0,1]
	v_pk_mul_f32 v[42:43], v[2:3], v[142:143] op_sel_hi:[1,0]
	v_pk_fma_f32 v[36:37], v[14:15], v[124:125], v[36:37] op_sel_hi:[1,0,1]
	v_pk_fma_f32 v[38:39], v[16:17], v[124:125], v[38:39] op_sel:[0,1,0]
	v_pk_fma_f32 v[42:43], v[4:5], v[142:143], v[42:43] op_sel:[0,1,0]
	v_pk_fma_f32 v[14:15], v[20:21], v[132:133], v[36:37] op_sel_hi:[1,0,1]
	v_pk_fma_f32 v[16:17], v[20:21], v[132:133], v[38:39] op_sel:[0,1,0]
	v_pk_fma_f32 v[42:43], v[6:7], v[144:145], v[42:43] op_sel_hi:[1,0,1]
	v_pk_fma_f32 v[42:43], v[8:9], v[144:145], v[42:43] op_sel:[0,1,0]
	v_pk_fma_f32 v[42:43], v[10:11], v[146:147], v[42:43] op_sel_hi:[1,0,1]
	v_pk_fma_f32 v[42:43], v[12:13], v[146:147], v[42:43] op_sel:[0,1,0]
	v_pk_fma_f32 v[42:43], v[14:15], v[148:149], v[42:43] op_sel_hi:[1,0,1]
	v_pk_fma_f32 v[42:43], v[16:17], v[148:149], v[42:43] op_sel:[0,1,0]
	s_waitcnt lgkmcnt(0)
; __device__ __forceinline__ void rwkv_block(KP p, int o, int b, int hd, LAS unsigned char* lds, const bf16_t* P, bf16_t* YB) {
;     ...
;             for (int tt = 0; tt < 16; ++tt) {
;                 const int o8 = tt * 64 + c * 8;
;                 const f32x4 ka = *(const LAS f32x4*)(KK + o8), kb = *(const LAS f32x4*)(KK + o8 + 4);
;                 const f32x4 wa = *(const LAS f32x4*)(Wd + o8), wb = *(const LAS f32x4*)(Wd + o8 + 4);
;                 const f32x4 ba = *(const LAS f32x4*)(BB + o8), bb = *(const LAS f32x4*)(BB + o8 + 4);
;                 const f32x4 ma = *(const LAS f32x4*)(KM + o8), mb = *(const LAS f32x4*)(KM + o8 + 4);
;                 const f32x4 ra = *(const LAS f32x4*)(Rr + o8), rb = *(const LAS f32x4*)(Rr + o8 + 4);
;                 const f32x2 v01 = *(const LAS f32x2*)(Vv + tt * 64 + 2 * rp);
;                 const f32x2 k2[4] = {{ka[0], ka[1]}, {ka[2], ka[3]}, {kb[0], kb[1]}, {kb[2], kb[3]}};
;                 const f32x2 w2[4] = {{wa[0], wa[1]}, {wa[2], wa[3]}, {wb[0], wb[1]}, {wb[2], wb[3]}};
;                 const f32x2 b2[4] = {{ba[0], ba[1]}, {ba[2], ba[3]}, {bb[0], bb[1]}, {bb[2], bb[3]}};
;                 const f32x2 m2[4] = {{ma[0], ma[1]}, {ma[2], ma[3]}, {mb[0], mb[1]}, {mb[2], mb[3]}};
;                 const f32x2 r2[4] = {{ra[0], ra[1]}, {ra[2], ra[3]}, {rb[0], rb[1]}, {rb[2], rb[3]}};
;                 f32x2 accA = s[0][0] * k2[0], accB = s[1][0] * k2[0], accA2 = s[0][2] * k2[2], accB2 = s[1][2] * k2[2];
;                 accA = s[0][1] * k2[1] + accA; accB = s[1][1] * k2[1] + accB; accA2 = s[0][3] * k2[3] + accA2; accB2 = s[1][3] * k2[3] + accB2;
;                 accA = accA + accA2; accB = accB + accB2;
;                 float sa0 = accA.x + accA.y, sa1 = accB.x + accB.y;
;                 sa0 += dpp_f<0xB1>(sa0); sa1 += dpp_f<0xB1>(sa1);
;                 sa0 += dpp_f<0x4E>(sa0); sa1 += dpp_f<0x4E>(sa1);
;                 sa0 += dpp_f<0x141>(sa0); sa1 += dpp_f<0x141>(sa1);
;                 const f32x2 saA = {sa0, sa0}, saB = {sa1, sa1}, vA = {v01.x, v01.x}, vB = {v01.y, v01.y};
;                 f32x2 yA, yB;
; #pragma unroll
;                 for (int j = 0; j < 4; ++j) {
;                     f32x2 tA = vA * m2[j], tB = vB * m2[j];
;                     tA = saA * b2[j] + tA; tB = saB * b2[j] + tB;
;                     s[0][j] = s[0][j] * w2[j] + tA; s[1][j] = s[1][j] * w2[j] + tB;
	v_pk_mul_f32 v[20:21], v[2:3], v[64:65] op_sel_hi:[1,0]
	ds_read_b128 v[110:113], v180 offset:7936
	ds_read_b128 v[114:117], v180 offset:7952
	v_pk_fma_f32 v[20:21], v[4:5], v[64:65], v[20:21] op_sel:[0,1,0]
	ds_read_b64 v[150:151], v181 offset:24320
	ds_read_b128 v[134:137], v180 offset:16128
	v_pk_fma_f32 v[20:21], v[6:7], v[66:67], v[20:21] op_sel_hi:[1,0,1]
	ds_read_b128 v[138:141], v180 offset:16144
	ds_read_b128 v[118:121], v180 offset:3840
	v_pk_fma_f32 v[20:21], v[8:9], v[66:67], v[20:21] op_sel:[0,1,0]
	ds_read_b128 v[122:125], v180 offset:3856
	ds_read_b128 v[126:129], v180 offset:12032
	v_pk_fma_f32 v[20:21], v[10:11], v[68:69], v[20:21] op_sel_hi:[1,0,1]
	ds_read_b128 v[130:133], v180 offset:12048
	ds_read_b128 v[142:145], v180 offset:20224
	v_pk_fma_f32 v[20:21], v[12:13], v[68:69], v[20:21] op_sel:[0,1,0]
	ds_read_b128 v[146:149], v180 offset:20240
	v_add_f32_dpp v42, v42, v42 quad_perm:[1,0,3,2] row_mask:0xf bank_mask:0xf bound_ctrl:1
	v_pk_fma_f32 v[20:21], v[14:15], v[70:71], v[20:21] op_sel_hi:[1,0,1]
	v_add_f32_dpp v43, v43, v43 quad_perm:[1,0,3,2] row_mask:0xf bank_mask:0xf bound_ctrl:1
	v_add_f32_dpp v42, v42, v42 quad_perm:[2,3,0,1] row_mask:0xf bank_mask:0xf bound_ctrl:1
	v_pk_fma_f32 v[20:21], v[16:17], v[70:71], v[20:21] op_sel:[0,1,0]
	v_add_f32_dpp v43, v43, v43 quad_perm:[2,3,0,1] row_mask:0xf bank_mask:0xf bound_ctrl:1
	v_add_f32_dpp v42, v42, v42 row_half_mirror row_mask:0xf bank_mask:0xf bound_ctrl:1
	v_add_f32_dpp v20, v20, v20 quad_perm:[1,0,3,2] row_mask:0xf bank_mask:0xf bound_ctrl:1
	v_add_f32_dpp v21, v21, v21 quad_perm:[1,0,3,2] row_mask:0xf bank_mask:0xf bound_ctrl:1
	v_add_f32_dpp v43, v43, v43 row_half_mirror row_mask:0xf bank_mask:0xf bound_ctrl:1
	v_add_f32_dpp v20, v20, v20 quad_perm:[2,3,0,1] row_mask:0xf bank_mask:0xf bound_ctrl:1
	v_add_f32_dpp v21, v21, v21 quad_perm:[2,3,0,1] row_mask:0xf bank_mask:0xf bound_ctrl:1
	ds_write_b64 v184, v[42:43] offset:32000
	v_add_f32_dpp v20, v20, v20 row_half_mirror row_mask:0xf bank_mask:0xf bound_ctrl:1
	v_add_f32_dpp v21, v21, v21 row_half_mirror row_mask:0xf bank_mask:0xf bound_ctrl:1
	v_pk_mul_f32 v[24:25], v[104:105], v[88:89] op_sel_hi:[1,0]
	v_pk_mul_f32 v[26:27], v[104:105], v[88:89] op_sel:[0,1]
	v_pk_mul_f32 v[28:29], v[104:105], v[90:91] op_sel_hi:[1,0]
	v_pk_fma_f32 v[24:25], v[2:3], v[72:73], v[24:25] op_sel_hi:[1,0,1]
	v_pk_fma_f32 v[26:27], v[4:5], v[72:73], v[26:27] op_sel:[0,1,0]
	v_pk_fma_f32 v[28:29], v[6:7], v[74:75], v[28:29] op_sel_hi:[1,0,1]
	v_pk_fma_f32 v[2:3], v[20:21], v[80:81], v[24:25] op_sel_hi:[1,0,1]
	v_pk_fma_f32 v[4:5], v[20:21], v[80:81], v[26:27] op_sel:[0,1,0]
	v_pk_fma_f32 v[6:7], v[20:21], v[82:83], v[28:29] op_sel_hi:[1,0,1]
	v_pk_mul_f32 v[30:31], v[104:105], v[90:91] op_sel:[0,1]
	v_pk_mul_f32 v[32:33], v[104:105], v[92:93] op_sel_hi:[1,0]
	v_pk_mul_f32 v[34:35], v[104:105], v[92:93] op_sel:[0,1]
	v_pk_fma_f32 v[30:31], v[8:9], v[74:75], v[30:31] op_sel:[0,1,0]
	v_pk_fma_f32 v[32:33], v[10:11], v[76:77], v[32:33] op_sel_hi:[1,0,1]
	v_pk_fma_f32 v[34:35], v[12:13], v[76:77], v[34:35] op_sel:[0,1,0]
	v_pk_fma_f32 v[8:9], v[20:21], v[82:83], v[30:31] op_sel:[0,1,0]
	v_pk_fma_f32 v[10:11], v[20:21], v[84:85], v[32:33] op_sel_hi:[1,0,1]
	v_pk_fma_f32 v[12:13], v[20:21], v[84:85], v[34:35] op_sel:[0,1,0]
	v_pk_mul_f32 v[36:37], v[104:105], v[94:95] op_sel_hi:[1,0]
	v_pk_mul_f32 v[38:39], v[104:105], v[94:95] op_sel:[0,1]
	v_pk_mul_f32 v[40:41], v[2:3], v[96:97] op_sel_hi:[1,0]
	v_pk_fma_f32 v[36:37], v[14:15], v[78:79], v[36:37] op_sel_hi:[1,0,1]
	v_pk_fma_f32 v[38:39], v[16:17], v[78:79], v[38:39] op_sel:[0,1,0]
	v_pk_fma_f32 v[40:41], v[4:5], v[96:97], v[40:41] op_sel:[0,1,0]
	v_pk_fma_f32 v[14:15], v[20:21], v[86:87], v[36:37] op_sel_hi:[1,0,1]
	v_pk_fma_f32 v[16:17], v[20:21], v[86:87], v[38:39] op_sel:[0,1,0]
	v_pk_fma_f32 v[40:41], v[6:7], v[98:99], v[40:41] op_sel_hi:[1,0,1]
	v_pk_fma_f32 v[40:41], v[8:9], v[98:99], v[40:41] op_sel:[0,1,0]
	v_pk_fma_f32 v[40:41], v[10:11], v[100:101], v[40:41] op_sel_hi:[1,0,1]
	v_pk_fma_f32 v[40:41], v[12:13], v[100:101], v[40:41] op_sel:[0,1,0]
	v_pk_fma_f32 v[40:41], v[14:15], v[102:103], v[40:41] op_sel_hi:[1,0,1]
	v_pk_fma_f32 v[40:41], v[16:17], v[102:103], v[40:41] op_sel:[0,1,0]
	s_waitcnt lgkmcnt(0)
; __device__ __forceinline__ void rwkv_block(KP p, int o, int b, int hd, LAS unsigned char* lds, const bf16_t* P, bf16_t* YB) {
;     ...
;             for (int tt = 0; tt < 16; ++tt) {
;                 const int o8 = tt * 64 + c * 8;
;                 const f32x4 ka = *(const LAS f32x4*)(KK + o8), kb = *(const LAS f32x4*)(KK + o8 + 4);
;                 const f32x4 wa = *(const LAS f32x4*)(Wd + o8), wb = *(const LAS f32x4*)(Wd + o8 + 4);
;                 const f32x4 ba = *(const LAS f32x4*)(BB + o8), bb = *(const LAS f32x4*)(BB + o8 + 4);
;                 const f32x4 ma = *(const LAS f32x4*)(KM + o8), mb = *(const LAS f32x4*)(KM + o8 + 4);
;                 const f32x4 ra = *(const LAS f32x4*)(Rr + o8), rb = *(const LAS f32x4*)(Rr + o8 + 4);
;                 const f32x2 v01 = *(const LAS f32x2*)(Vv + tt * 64 + 2 * rp);
;                 const f32x2 k2[4] = {{ka[0], ka[1]}, {ka[2], ka[3]}, {kb[0], kb[1]}, {kb[2], kb[3]}};
;                 const f32x2 w2[4] = {{wa[0], wa[1]}, {wa[2], wa[3]}, {wb[0], wb[1]}, {wb[2], wb[3]}};
;                 const f32x2 b2[4] = {{ba[0], ba[1]}, {ba[2], ba[3]}, {bb[0], bb[1]}, {bb[2], bb[3]}};
;                 const f32x2 m2[4] = {{ma[0], ma[1]}, {ma[2], ma[3]}, {mb[0], mb[1]}, {mb[2], mb[3]}};
;                 const f32x2 r2[4] = {{ra[0], ra[1]}, {ra[2], ra[3]}, {rb[0], rb[1]}, {rb[2], rb[3]}};
;                 f32x2 accA = s[0][0] * k2[0], accB = s[1][0] * k2[0], accA2 = s[0][2] * k2[2], accB2 = s[1][2] * k2[2];
;                 accA = s[0][1] * k2[1] + accA; accB = s[1][1] * k2[1] + accB; accA2 = s[0][3] * k2[3] + accA2; accB2 = s[1][3] * k2[3] + accB2;
;                 accA = accA + accA2; accB = accB + accB2;
;                 float sa0 = accA.x + accA.y, sa1 = accB.x + accB.y;
;                 sa0 += dpp_f<0xB1>(sa0); sa1 += dpp_f<0xB1>(sa1);
;                 sa0 += dpp_f<0x4E>(sa0); sa1 += dpp_f<0x4E>(sa1);
;                 sa0 += dpp_f<0x141>(sa0); sa1 += dpp_f<0x141>(sa1);
;                 const f32x2 saA = {sa0, sa0}, saB = {sa1, sa1}, vA = {v01.x, v01.x}, vB = {v01.y, v01.y};
;                 f32x2 yA, yB;
; #pragma unroll
;                 for (int j = 0; j < 4; ++j) {
;                     f32x2 tA = vA * m2[j], tB = vB * m2[j];
;                     tA = saA * b2[j] + tA; tB = saB * b2[j] + tB;
;                     s[0][j] = s[0][j] * w2[j] + tA; s[1][j] = s[1][j] * w2[j] + tB;
	v_pk_mul_f32 v[20:21], v[2:3], v[110:111] op_sel_hi:[1,0]
	v_add_f32_dpp v40, v40, v40 quad_perm:[1,0,3,2] row_mask:0xf bank_mask:0xf bound_ctrl:1
	v_add_f32_dpp v41, v41, v41 quad_perm:[1,0,3,2] row_mask:0xf bank_mask:0xf bound_ctrl:1
	v_pk_fma_f32 v[20:21], v[4:5], v[110:111], v[20:21] op_sel:[0,1,0]
	v_add_f32_dpp v40, v40, v40 quad_perm:[2,3,0,1] row_mask:0xf bank_mask:0xf bound_ctrl:1
	v_add_f32_dpp v41, v41, v41 quad_perm:[2,3,0,1] row_mask:0xf bank_mask:0xf bound_ctrl:1
	v_pk_fma_f32 v[20:21], v[6:7], v[112:113], v[20:21] op_sel_hi:[1,0,1]
	v_add_f32_dpp v40, v40, v40 row_half_mirror row_mask:0xf bank_mask:0xf bound_ctrl:1
	v_add_f32_dpp v41, v41, v41 row_half_mirror row_mask:0xf bank_mask:0xf bound_ctrl:1
	v_pk_fma_f32 v[20:21], v[8:9], v[112:113], v[20:21] op_sel:[0,1,0]
	v_pk_mul_f32 v[24:25], v[150:151], v[134:135] op_sel_hi:[1,0]
	ds_write_b64 v184, v[40:41] offset:32256
	v_pk_fma_f32 v[20:21], v[10:11], v[114:115], v[20:21] op_sel_hi:[1,0,1]
	v_pk_fma_f32 v[24:25], v[2:3], v[118:119], v[24:25] op_sel_hi:[1,0,1]
	v_pk_mul_f32 v[26:27], v[150:151], v[134:135] op_sel:[0,1]
	v_pk_fma_f32 v[20:21], v[12:13], v[114:115], v[20:21] op_sel:[0,1,0]
	v_pk_mul_f32 v[28:29], v[150:151], v[136:137] op_sel_hi:[1,0]
	v_pk_fma_f32 v[26:27], v[4:5], v[118:119], v[26:27] op_sel:[0,1,0]
	v_pk_fma_f32 v[20:21], v[14:15], v[116:117], v[20:21] op_sel_hi:[1,0,1]
	v_pk_fma_f32 v[28:29], v[6:7], v[120:121], v[28:29] op_sel_hi:[1,0,1]
	v_pk_mul_f32 v[30:31], v[150:151], v[136:137] op_sel:[0,1]
	v_pk_fma_f32 v[20:21], v[16:17], v[116:117], v[20:21] op_sel:[0,1,0]
	v_pk_mul_f32 v[32:33], v[150:151], v[138:139] op_sel_hi:[1,0]
	v_pk_fma_f32 v[30:31], v[8:9], v[120:121], v[30:31] op_sel:[0,1,0]
	v_add_f32_dpp v20, v20, v20 quad_perm:[1,0,3,2] row_mask:0xf bank_mask:0xf bound_ctrl:1
	v_add_f32_dpp v21, v21, v21 quad_perm:[1,0,3,2] row_mask:0xf bank_mask:0xf bound_ctrl:1
	v_pk_fma_f32 v[32:33], v[10:11], v[122:123], v[32:33] op_sel_hi:[1,0,1]
	v_add_f32_dpp v20, v20, v20 quad_perm:[2,3,0,1] row_mask:0xf bank_mask:0xf bound_ctrl:1
	v_add_f32_dpp v21, v21, v21 quad_perm:[2,3,0,1] row_mask:0xf bank_mask:0xf bound_ctrl:1
	v_pk_mul_f32 v[34:35], v[150:151], v[138:139] op_sel:[0,1]
	v_add_f32_dpp v20, v20, v20 row_half_mirror row_mask:0xf bank_mask:0xf bound_ctrl:1
	v_add_f32_dpp v21, v21, v21 row_half_mirror row_mask:0xf bank_mask:0xf bound_ctrl:1
	v_pk_fma_f32 v[34:35], v[12:13], v[122:123], v[34:35] op_sel:[0,1,0]
	v_pk_mul_f32 v[36:37], v[150:151], v[140:141] op_sel_hi:[1,0]
	v_pk_fma_f32 v[2:3], v[20:21], v[126:127], v[24:25] op_sel_hi:[1,0,1]
	v_pk_fma_f32 v[4:5], v[20:21], v[126:127], v[26:27] op_sel:[0,1,0]
	v_pk_fma_f32 v[6:7], v[20:21], v[128:129], v[28:29] op_sel_hi:[1,0,1]
	v_pk_fma_f32 v[8:9], v[20:21], v[128:129], v[30:31] op_sel:[0,1,0]
	v_pk_fma_f32 v[10:11], v[20:21], v[130:131], v[32:33] op_sel_hi:[1,0,1]
	v_pk_fma_f32 v[12:13], v[20:21], v[130:131], v[34:35] op_sel:[0,1,0]
	v_pk_fma_f32 v[36:37], v[14:15], v[124:125], v[36:37] op_sel_hi:[1,0,1]
	v_pk_mul_f32 v[38:39], v[150:151], v[140:141] op_sel:[0,1]
	v_pk_mul_f32 v[42:43], v[2:3], v[142:143] op_sel_hi:[1,0]
	v_pk_fma_f32 v[14:15], v[20:21], v[132:133], v[36:37] op_sel_hi:[1,0,1]
	v_pk_fma_f32 v[38:39], v[16:17], v[124:125], v[38:39] op_sel:[0,1,0]
	v_pk_fma_f32 v[42:43], v[4:5], v[142:143], v[42:43] op_sel:[0,1,0]
	v_pk_fma_f32 v[16:17], v[20:21], v[132:133], v[38:39] op_sel:[0,1,0]
	v_pk_fma_f32 v[42:43], v[6:7], v[144:145], v[42:43] op_sel_hi:[1,0,1]
	v_pk_fma_f32 v[42:43], v[8:9], v[144:145], v[42:43] op_sel:[0,1,0]
	v_pk_fma_f32 v[42:43], v[10:11], v[146:147], v[42:43] op_sel_hi:[1,0,1]
	v_pk_fma_f32 v[42:43], v[12:13], v[146:147], v[42:43] op_sel:[0,1,0]
	v_pk_fma_f32 v[42:43], v[14:15], v[148:149], v[42:43] op_sel_hi:[1,0,1]
	v_pk_fma_f32 v[42:43], v[16:17], v[148:149], v[42:43] op_sel:[0,1,0]
	s_nop 1
	v_add_f32_dpp v42, v42, v42 quad_perm:[1,0,3,2] row_mask:0xf bank_mask:0xf bound_ctrl:1
	v_add_f32_dpp v43, v43, v43 quad_perm:[1,0,3,2] row_mask:0xf bank_mask:0xf bound_ctrl:1
	s_nop 0
	v_add_f32_dpp v42, v42, v42 quad_perm:[2,3,0,1] row_mask:0xf bank_mask:0xf bound_ctrl:1
	v_add_f32_dpp v43, v43, v43 quad_perm:[2,3,0,1] row_mask:0xf bank_mask:0xf bound_ctrl:1
	s_nop 0
	v_add_f32_dpp v42, v42, v42 row_half_mirror row_mask:0xf bank_mask:0xf bound_ctrl:1
	v_add_f32_dpp v43, v43, v43 row_half_mirror row_mask:0xf bank_mask:0xf bound_ctrl:1
	ds_write_b64 v184, v[42:43] offset:32512
	s_waitcnt lgkmcnt(0)
	s_barrier
	s_add_i32 s1, s1, 1
	s_cmpk_eq_i32 s1, 0x100
	s_cbranch_scc0 .Lrk_scan_loop
	s_setprio 0
	s_branch .LBB0_156
